# KV-up epilogue: the eight per-row rstd partial loads issued ahead (were one round trip each, each wait also draining all stores); its flat stores made global
# baseline (speedup 1.0000x reference)
; #define G_STAGE(bufoff, gbase, voff) do { _Pragma("unroll") for (int _i = 0; _i < 2; ++_i) \
;         __builtin_amdgcn_global_load_lds((const unsigned*)((const char*)(gbase) + (voff)[_i]), (LAS unsigned*)(lds + (bufoff) + ldsw + _i * 8192), 16, 0, 0); } while (0)
; #define G_LDA(dst, b, h) do { _Pragma("unroll") for (int m = 0; m < 4; ++m) _Pragma("unroll") for (int k = 0; k < 2; ++k) dst[m][k] = *(const LAS bf16x8*)(lds + G_SA(b, h) + aoff + m * 2048 + k * 1024); } while (0)
; #define G_LDB(dst, b, h) do { _Pragma("unroll") for (int n = 0; n < 2; ++n) _Pragma("unroll") for (int k = 0; k < 2; ++k) dst[n][k] = *(const LAS bf16x8*)(lds + G_SB(b, h) + boff + n * 2048 + k * 1024); } while (0)
; #define G_MMA(ai, bj, At, Bt_) do { __builtin_amdgcn_s_setprio(1); _Pragma("unroll") for (int m = 0; m < 4; ++m) _Pragma("unroll") for (int n = 0; n < 2; ++n) _Pragma("unroll") for (int k = 0; k < 2; ++k) \
;         acc[ai][bj][m][n] = __builtin_amdgcn_mfma_f32_16x16x32_bf16(Bt_[n][k], At[m][k], acc[ai][bj][m][n], 0, 0, 0); __builtin_amdgcn_s_setprio(0); } while (0)
; template <class Epi, bool PERMROWS = false>
; DI void gemm_phase(LAS unsigned char* lds, const bf16_t* A, int lda, const bf16_t* Bt, int K, const Sched& S, const Epi& E) {
;     ...
;             G_LDB(B0, 0, 0); G_SCHED; G_LDA(At, 0, 0); G_STAGE(G_SA(1, 1), a1 + hstepA, voffA);
;             G_WAIT_L(8); G_BAR; G_WAIT_L(0); G_MMA(0, 0, At, B0); G_BAR; G_SCHED;
;             G_LDB(B1, 0, 1); G_STAGE(G_SB(0, 0), b2, voffB);
;             G_BAR; G_WAIT_L(0); G_MMA(0, 1, At, B1); G_BAR;
;             G_LDA(At, 0, 1); G_STAGE(G_SA(0, 0), a2, voffA);
;             G_BAR; G_WAIT_L(0); G_MMA(1, 0, At, B0); G_BAR; G_SCHED;
;             G_STAGE(G_SB(0, 1), b2 + hstepB, voffB);
;             G_WAIT_V(6); G_BAR; G_MMA(1, 1, At, B1); G_BAR;
;             G_LDB(B0, 1, 0); G_SCHED; G_LDA(At, 1, 0); G_STAGE(G_SA(0, 1), a2 + hstepA, voffA);
;             G_WAIT_L(8); G_BAR; G_WAIT_L(0); G_MMA(0, 0, At, B0); G_BAR; G_SCHED;
;             G_LDB(B1, 1, 1); G_STAGE(G_SB(1, 0), b3, voffB);
;             G_BAR; G_WAIT_L(0); G_MMA(0, 1, At, B1); G_BAR;
;             G_LDA(At, 1, 1); G_STAGE(G_SA(1, 0), a3, voffA);
;             G_BAR; G_WAIT_L(0); G_MMA(1, 0, At, B0); G_BAR; G_SCHED;
;             G_STAGE(G_SB(1, 1), b3 + hstepB, voffB);
;             G_WAIT_V(6); G_BAR; G_MMA(1, 1, At, B1); G_BAR;
.LBB0_1071:
	ds_read_b128 v[150:153], v157
	ds_read_b128 v[164:167], v157 offset:1024
	ds_read_b128 v[168:171], v157 offset:2048
	ds_read_b128 v[172:175], v157 offset:3072
	s_add_u32 s0, s20, 0x100
	s_addc_u32 s1, s21, 0
	s_cmp_eq_u32 s28, 4
	s_cselect_b32 s23, s17, s1
	s_cselect_b32 s22, s16, s0
	s_cselect_b32 s9, s15, s83
	s_cselect_b32 s8, s81, s82
	v_lshl_add_u64 v[154:155], s[20:21], 0, v[144:145]
	s_add_i32 m0, s34, 0xc000
	ds_read_b128 v[176:179], v158
	ds_read_b128 v[180:183], v158 offset:1024
	ds_read_b128 v[184:187], v158 offset:2048
	ds_read_b128 v[188:191], v158 offset:3072
	ds_read_b128 v[192:195], v158 offset:4096
	ds_read_b128 v[196:199], v158 offset:5120
	ds_read_b128 v[204:207], v158 offset:6144
	ds_read_b128 v[208:211], v158 offset:7168
	global_load_lds_dwordx4 v[154:155], off
	v_lshl_add_u64 v[154:155], s[20:21], 0, v[142:143]
	s_add_i32 m0, s34, 0xe000
	s_nop 0
	global_load_lds_dwordx4 v[154:155], off
	s_waitcnt lgkmcnt(8)
	s_barrier
	s_waitcnt lgkmcnt(0)
	s_setprio 1
	s_waitcnt lgkmcnt(0)
	v_mfma_f32_16x16x32_bf16 v[124:127], v[150:153], v[176:179], v[124:127]
	v_mfma_f32_16x16x32_bf16 v[120:123], v[168:171], v[176:179], v[120:123]
	v_mfma_f32_16x16x32_bf16 v[108:111], v[150:153], v[184:187], v[108:111]
	v_mfma_f32_16x16x32_bf16 v[104:107], v[168:171], v[184:187], v[104:107]
	v_mfma_f32_16x16x32_bf16 v[92:95], v[150:153], v[192:195], v[92:95]
	v_mfma_f32_16x16x32_bf16 v[88:91], v[168:171], v[192:195], v[88:91]
	v_mfma_f32_16x16x32_bf16 v[76:79], v[150:153], v[204:207], v[76:79]
	v_mfma_f32_16x16x32_bf16 v[72:75], v[168:171], v[204:207], v[72:75]
	v_mfma_f32_16x16x32_bf16 v[124:127], v[164:167], v[180:183], v[124:127]
	v_mfma_f32_16x16x32_bf16 v[120:123], v[172:175], v[180:183], v[120:123]
	v_mfma_f32_16x16x32_bf16 v[108:111], v[164:167], v[188:191], v[108:111]
	v_mfma_f32_16x16x32_bf16 v[104:107], v[172:175], v[188:191], v[104:107]
	v_mfma_f32_16x16x32_bf16 v[92:95], v[164:167], v[196:199], v[92:95]
	v_mfma_f32_16x16x32_bf16 v[88:91], v[172:175], v[196:199], v[88:91]
	v_mfma_f32_16x16x32_bf16 v[76:79], v[164:167], v[208:211], v[76:79]
	v_mfma_f32_16x16x32_bf16 v[72:75], v[172:175], v[208:211], v[72:75]
	s_setprio 0
	s_barrier
	s_add_i32 s20, s63, s31
	v_lshl_add_u64 v[154:155], s[8:9], 0, v[130:131]
	s_mov_b32 m0, s20
	ds_read_b128 v[212:215], v159
	ds_read_b128 v[216:219], v159 offset:1024
	ds_read_b128 v[220:223], v159 offset:2048
	ds_read_b128 v[224:227], v159 offset:3072
	global_load_lds_dwordx4 v[154:155], off
	v_lshl_add_u64 v[200:201], s[8:9], 0, v[134:135]
	s_add_i32 m0, s20, 0x2000
	s_nop 0
	global_load_lds_dwordx4 v[200:201], off
	s_barrier
	s_waitcnt lgkmcnt(0)
	s_setprio 1
	s_waitcnt lgkmcnt(0)
	v_mfma_f32_16x16x32_bf16 v[116:119], v[212:215], v[176:179], v[116:119]
	v_mfma_f32_16x16x32_bf16 v[112:115], v[220:223], v[176:179], v[112:115]
	v_mfma_f32_16x16x32_bf16 v[100:103], v[212:215], v[184:187], v[100:103]
	v_mfma_f32_16x16x32_bf16 v[96:99], v[220:223], v[184:187], v[96:99]
	v_mfma_f32_16x16x32_bf16 v[84:87], v[212:215], v[192:195], v[84:87]
	v_mfma_f32_16x16x32_bf16 v[80:83], v[220:223], v[192:195], v[80:83]
	v_mfma_f32_16x16x32_bf16 v[68:71], v[212:215], v[204:207], v[68:71]
	v_mfma_f32_16x16x32_bf16 v[64:67], v[220:223], v[204:207], v[64:67]
	v_mfma_f32_16x16x32_bf16 v[116:119], v[216:219], v[180:183], v[116:119]
	v_mfma_f32_16x16x32_bf16 v[112:115], v[224:227], v[180:183], v[112:115]
	v_mfma_f32_16x16x32_bf16 v[100:103], v[216:219], v[188:191], v[100:103]
	v_mfma_f32_16x16x32_bf16 v[96:99], v[224:227], v[188:191], v[96:99]
	v_mfma_f32_16x16x32_bf16 v[84:87], v[216:219], v[196:199], v[84:87]
	v_mfma_f32_16x16x32_bf16 v[80:83], v[224:227], v[196:199], v[80:83]
	v_mfma_f32_16x16x32_bf16 v[68:71], v[216:219], v[208:211], v[68:71]
	v_mfma_f32_16x16x32_bf16 v[64:67], v[224:227], v[208:211], v[64:67]
	s_setprio 0
	s_mov_b32 m0, s34
	v_lshl_add_u64 v[228:229], s[22:23], 0, v[128:129]
	s_barrier
	ds_read_b128 v[176:179], v158 offset:16384
	ds_read_b128 v[180:183], v158 offset:17408
	ds_read_b128 v[184:187], v158 offset:18432
	ds_read_b128 v[188:191], v158 offset:19456
	ds_read_b128 v[192:195], v158 offset:20480
	ds_read_b128 v[196:199], v158 offset:21504
	ds_read_b128 v[204:207], v158 offset:22528
	ds_read_b128 v[208:211], v158 offset:23552
	global_load_lds_dwordx4 v[228:229], off
	v_lshl_add_u64 v[230:231], s[22:23], 0, v[132:133]
	s_mov_b32 m0, s35
	s_nop 0
	global_load_lds_dwordx4 v[230:231], off
	s_barrier
	s_waitcnt lgkmcnt(0)
	s_setprio 1
	s_waitcnt lgkmcnt(0)
	v_mfma_f32_16x16x32_bf16 v[60:63], v[150:153], v[176:179], v[60:63]
	v_mfma_f32_16x16x32_bf16 v[56:59], v[168:171], v[176:179], v[56:59]
	v_mfma_f32_16x16x32_bf16 v[44:47], v[150:153], v[184:187], v[44:47]
	v_mfma_f32_16x16x32_bf16 v[40:43], v[168:171], v[184:187], v[40:43]
	v_mfma_f32_16x16x32_bf16 v[28:31], v[150:153], v[192:195], v[28:31]
	v_mfma_f32_16x16x32_bf16 v[24:27], v[168:171], v[192:195], v[24:27]
	v_mfma_f32_16x16x32_bf16 v[12:15], v[150:153], v[204:207], v[12:15]
	v_mfma_f32_16x16x32_bf16 v[8:11], v[168:171], v[204:207], v[8:11]
	v_mfma_f32_16x16x32_bf16 v[60:63], v[164:167], v[180:183], v[60:63]
	v_mfma_f32_16x16x32_bf16 v[56:59], v[172:175], v[180:183], v[56:59]
	v_mfma_f32_16x16x32_bf16 v[44:47], v[164:167], v[188:191], v[44:47]
	v_mfma_f32_16x16x32_bf16 v[40:43], v[172:175], v[188:191], v[40:43]
	v_mfma_f32_16x16x32_bf16 v[28:31], v[164:167], v[196:199], v[28:31]
	v_mfma_f32_16x16x32_bf16 v[24:27], v[172:175], v[196:199], v[24:27]
	v_mfma_f32_16x16x32_bf16 v[12:15], v[164:167], v[208:211], v[12:15]
	v_mfma_f32_16x16x32_bf16 v[8:11], v[172:175], v[208:211], v[8:11]
	s_setprio 0
	s_barrier
; #define G_STAGE(bufoff, gbase, voff) do { _Pragma("unroll") for (int _i = 0; _i < 2; ++_i) \
;         __builtin_amdgcn_global_load_lds((const unsigned*)((const char*)(gbase) + (voff)[_i]), (LAS unsigned*)(lds + (bufoff) + ldsw + _i * 8192), 16, 0, 0); } while (0)
; #define G_LDA(dst, b, h) do { _Pragma("unroll") for (int m = 0; m < 4; ++m) _Pragma("unroll") for (int k = 0; k < 2; ++k) dst[m][k] = *(const LAS bf16x8*)(lds + G_SA(b, h) + aoff + m * 2048 + k * 1024); } while (0)
; #define G_LDB(dst, b, h) do { _Pragma("unroll") for (int n = 0; n < 2; ++n) _Pragma("unroll") for (int k = 0; k < 2; ++k) dst[n][k] = *(const LAS bf16x8*)(lds + G_SB(b, h) + boff + n * 2048 + k * 1024); } while (0)
; #define G_MMA(ai, bj, At, Bt_) do { __builtin_amdgcn_s_setprio(1); _Pragma("unroll") for (int m = 0; m < 4; ++m) _Pragma("unroll") for (int n = 0; n < 2; ++n) _Pragma("unroll") for (int k = 0; k < 2; ++k) \
;         acc[ai][bj][m][n] = __builtin_amdgcn_mfma_f32_16x16x32_bf16(Bt_[n][k], At[m][k], acc[ai][bj][m][n], 0, 0, 0); __builtin_amdgcn_s_setprio(0); } while (0)
; template <class Epi, bool PERMROWS = false>
; DI void gemm_phase(LAS unsigned char* lds, const bf16_t* A, int lda, const bf16_t* Bt, int K, const Sched& S, const Epi& E) {
;     ...
;             G_LDB(B0, 0, 0); G_SCHED; G_LDA(At, 0, 0); G_STAGE(G_SA(1, 1), a1 + hstepA, voffA);
;             G_WAIT_L(8); G_BAR; G_WAIT_L(0); G_MMA(0, 0, At, B0); G_BAR; G_SCHED;
;             G_LDB(B1, 0, 1); G_STAGE(G_SB(0, 0), b2, voffB);
;             G_BAR; G_WAIT_L(0); G_MMA(0, 1, At, B1); G_BAR;
;             G_LDA(At, 0, 1); G_STAGE(G_SA(0, 0), a2, voffA);
;             G_BAR; G_WAIT_L(0); G_MMA(1, 0, At, B0); G_BAR; G_SCHED;
;             G_STAGE(G_SB(0, 1), b2 + hstepB, voffB);
;             G_WAIT_V(6); G_BAR; G_MMA(1, 1, At, B1); G_BAR;
;             G_LDB(B0, 1, 0); G_SCHED; G_LDA(At, 1, 0); G_STAGE(G_SA(0, 1), a2 + hstepA, voffA);
;             G_WAIT_L(8); G_BAR; G_WAIT_L(0); G_MMA(0, 0, At, B0); G_BAR; G_SCHED;
;             G_LDB(B1, 1, 1); G_STAGE(G_SB(1, 0), b3, voffB);
;             G_BAR; G_WAIT_L(0); G_MMA(0, 1, At, B1); G_BAR;
;             G_LDA(At, 1, 1); G_STAGE(G_SA(1, 0), a3, voffA);
;             G_BAR; G_WAIT_L(0); G_MMA(1, 0, At, B0); G_BAR; G_SCHED;
;             G_STAGE(G_SB(1, 1), b3 + hstepB, voffB);
;             G_WAIT_V(6); G_BAR; G_MMA(1, 1, At, B1); G_BAR;
	s_add_u32 s20, s8, 0x20000
	s_addc_u32 s21, s9, 0
	s_add_i32 s29, s68, s31
	v_lshl_add_u64 v[150:151], s[20:21], 0, v[130:131]
	s_mov_b32 m0, s29
	s_nop 0
	global_load_lds_dwordx4 v[150:151], off
	v_lshl_add_u64 v[150:151], s[20:21], 0, v[134:135]
	s_add_i32 m0, s29, 0x2000
	s_nop 0
	global_load_lds_dwordx4 v[150:151], off
	s_waitcnt vmcnt(6)
	s_barrier
	s_setprio 1
	v_mfma_f32_16x16x32_bf16 v[52:55], v[212:215], v[176:179], v[52:55]
	v_mfma_f32_16x16x32_bf16 v[48:51], v[220:223], v[176:179], v[48:51]
	v_mfma_f32_16x16x32_bf16 v[36:39], v[212:215], v[184:187], v[36:39]
	v_mfma_f32_16x16x32_bf16 v[32:35], v[220:223], v[184:187], v[32:35]
	v_mfma_f32_16x16x32_bf16 v[20:23], v[212:215], v[192:195], v[20:23]
	v_mfma_f32_16x16x32_bf16 v[16:19], v[220:223], v[192:195], v[16:19]
	v_mfma_f32_16x16x32_bf16 v[4:7], v[212:215], v[204:207], v[4:7]
	v_mfma_f32_16x16x32_bf16 v[0:3], v[220:223], v[204:207], v[0:3]
	v_mfma_f32_16x16x32_bf16 v[52:55], v[216:219], v[180:183], v[52:55]
	v_mfma_f32_16x16x32_bf16 v[48:51], v[224:227], v[180:183], v[48:51]
	v_mfma_f32_16x16x32_bf16 v[36:39], v[216:219], v[188:191], v[36:39]
	v_mfma_f32_16x16x32_bf16 v[32:35], v[224:227], v[188:191], v[32:35]
	v_mfma_f32_16x16x32_bf16 v[20:23], v[216:219], v[196:199], v[20:23]
	v_mfma_f32_16x16x32_bf16 v[16:19], v[224:227], v[196:199], v[16:19]
	v_mfma_f32_16x16x32_bf16 v[4:7], v[216:219], v[208:211], v[4:7]
	v_mfma_f32_16x16x32_bf16 v[0:3], v[224:227], v[208:211], v[0:3]
	s_setprio 0
	s_add_i32 s29, 0, 0x18000
	v_add_u32_e32 v163, s29, v156
	s_barrier
	ds_read_b128 v[150:153], v163
	ds_read_b128 v[164:167], v163 offset:1024
	ds_read_b128 v[168:171], v163 offset:2048
	ds_read_b128 v[172:175], v163 offset:3072
	s_add_u32 s20, s22, 0x180000
	s_addc_u32 s21, s23, 0
	s_mov_b32 m0, s36
	v_lshl_add_u64 v[212:213], s[20:21], 0, v[128:129]
	ds_read_b128 v[176:179], v158 offset:32768
	ds_read_b128 v[180:183], v158 offset:33792
	ds_read_b128 v[184:187], v158 offset:34816
	ds_read_b128 v[188:191], v158 offset:35840
	ds_read_b128 v[192:195], v158 offset:36864
	ds_read_b128 v[196:199], v158 offset:37888
	ds_read_b128 v[204:207], v158 offset:38912
	ds_read_b128 v[208:211], v158 offset:39936
	global_load_lds_dwordx4 v[212:213], off
	v_lshl_add_u64 v[212:213], s[20:21], 0, v[132:133]
	s_mov_b32 m0, s37
	s_nop 0
	global_load_lds_dwordx4 v[212:213], off
	s_waitcnt lgkmcnt(8)
	s_barrier
	s_waitcnt lgkmcnt(0)
	s_setprio 1
	s_waitcnt lgkmcnt(0)
	v_mfma_f32_16x16x32_bf16 v[124:127], v[150:153], v[176:179], v[124:127]
	v_mfma_f32_16x16x32_bf16 v[120:123], v[168:171], v[176:179], v[120:123]
	v_mfma_f32_16x16x32_bf16 v[108:111], v[150:153], v[184:187], v[108:111]
	v_mfma_f32_16x16x32_bf16 v[104:107], v[168:171], v[184:187], v[104:107]
	v_mfma_f32_16x16x32_bf16 v[92:95], v[150:153], v[192:195], v[92:95]
	v_mfma_f32_16x16x32_bf16 v[88:91], v[168:171], v[192:195], v[88:91]
	v_mfma_f32_16x16x32_bf16 v[76:79], v[150:153], v[204:207], v[76:79]
	v_mfma_f32_16x16x32_bf16 v[72:75], v[168:171], v[204:207], v[72:75]
	v_mfma_f32_16x16x32_bf16 v[124:127], v[164:167], v[180:183], v[124:127]
	v_mfma_f32_16x16x32_bf16 v[120:123], v[172:175], v[180:183], v[120:123]
	v_mfma_f32_16x16x32_bf16 v[108:111], v[164:167], v[188:191], v[108:111]
	v_mfma_f32_16x16x32_bf16 v[104:107], v[172:175], v[188:191], v[104:107]
	v_mfma_f32_16x16x32_bf16 v[92:95], v[164:167], v[196:199], v[92:95]
	v_mfma_f32_16x16x32_bf16 v[88:91], v[172:175], v[196:199], v[88:91]
	v_mfma_f32_16x16x32_bf16 v[76:79], v[164:167], v[208:211], v[76:79]
	v_mfma_f32_16x16x32_bf16 v[72:75], v[172:175], v[208:211], v[72:75]
	s_setprio 0
	s_barrier
	s_add_i32 s20, 0, 0x1c000
	s_add_i32 s21, s29, s31
	v_add_u32_e32 v163, s20, v156
	v_lshl_add_u64 v[154:155], v[154:155], 0, s[10:11]
	s_mov_b32 m0, s21
	ds_read_b128 v[212:215], v163
	ds_read_b128 v[216:219], v163 offset:1024
	ds_read_b128 v[220:223], v163 offset:2048
	ds_read_b128 v[224:227], v163 offset:3072
	global_load_lds_dwordx4 v[154:155], off
	v_lshl_add_u64 v[154:155], v[200:201], 0, s[10:11]
	s_add_i32 m0, s21, 0x2000
	s_nop 0
	global_load_lds_dwordx4 v[154:155], off
	s_barrier
	s_waitcnt lgkmcnt(0)
	s_setprio 1
	s_waitcnt lgkmcnt(0)
	v_mfma_f32_16x16x32_bf16 v[116:119], v[212:215], v[176:179], v[116:119]
	v_mfma_f32_16x16x32_bf16 v[112:115], v[220:223], v[176:179], v[112:115]
	v_mfma_f32_16x16x32_bf16 v[100:103], v[212:215], v[184:187], v[100:103]
	v_mfma_f32_16x16x32_bf16 v[96:99], v[220:223], v[184:187], v[96:99]
	v_mfma_f32_16x16x32_bf16 v[84:87], v[212:215], v[192:195], v[84:87]
	v_mfma_f32_16x16x32_bf16 v[80:83], v[220:223], v[192:195], v[80:83]
	v_mfma_f32_16x16x32_bf16 v[68:71], v[212:215], v[204:207], v[68:71]
	v_mfma_f32_16x16x32_bf16 v[64:67], v[220:223], v[204:207], v[64:67]
	v_mfma_f32_16x16x32_bf16 v[116:119], v[216:219], v[180:183], v[116:119]
	v_mfma_f32_16x16x32_bf16 v[112:115], v[224:227], v[180:183], v[112:115]
	v_mfma_f32_16x16x32_bf16 v[100:103], v[216:219], v[188:191], v[100:103]
	v_mfma_f32_16x16x32_bf16 v[96:99], v[224:227], v[188:191], v[96:99]
	v_mfma_f32_16x16x32_bf16 v[84:87], v[216:219], v[196:199], v[84:87]
	v_mfma_f32_16x16x32_bf16 v[80:83], v[224:227], v[196:199], v[80:83]
	v_mfma_f32_16x16x32_bf16 v[68:71], v[216:219], v[208:211], v[68:71]
	v_mfma_f32_16x16x32_bf16 v[64:67], v[224:227], v[208:211], v[64:67]
	s_setprio 0
	s_mov_b32 m0, s56
	v_lshl_add_u64 v[154:155], v[228:229], 0, s[10:11]
	s_barrier
	ds_read_b128 v[176:179], v158 offset:49152
	ds_read_b128 v[180:183], v158 offset:50176
	ds_read_b128 v[184:187], v158 offset:51200
	ds_read_b128 v[188:191], v158 offset:52224
	ds_read_b128 v[192:195], v158 offset:53248
	ds_read_b128 v[196:199], v158 offset:54272
	ds_read_b128 v[204:207], v158 offset:55296
	ds_read_b128 v[208:211], v158 offset:56320
	global_load_lds_dwordx4 v[154:155], off
	v_lshl_add_u64 v[154:155], v[230:231], 0, s[10:11]
	s_mov_b32 m0, s57
	s_nop 0
	global_load_lds_dwordx4 v[154:155], off
	s_barrier
; #define G_STAGE(bufoff, gbase, voff) do { _Pragma("unroll") for (int _i = 0; _i < 2; ++_i) \
;         __builtin_amdgcn_global_load_lds((const unsigned*)((const char*)(gbase) + (voff)[_i]), (LAS unsigned*)(lds + (bufoff) + ldsw + _i * 8192), 16, 0, 0); } while (0)
; #define G_LDA(dst, b, h) do { _Pragma("unroll") for (int m = 0; m < 4; ++m) _Pragma("unroll") for (int k = 0; k < 2; ++k) dst[m][k] = *(const LAS bf16x8*)(lds + G_SA(b, h) + aoff + m * 2048 + k * 1024); } while (0)
; #define G_WAIT_V(n) asm volatile("s_waitcnt vmcnt(" #n ")" ::: "memory")
; #define G_WAIT_L(n) asm volatile("s_waitcnt lgkmcnt(" #n ")" ::: "memory")
; #define G_BAR __builtin_amdgcn_s_barrier()
; template <class Epi, bool PERMROWS = false>
; DI void gemm_phase(LAS unsigned char* lds, const bf16_t* A, int lda, const bf16_t* Bt, int K, const Sched& S, const Epi& E) {
;     ...
;             G_WAIT_V(6); G_BAR; G_MMA(1, 1, At, B1); G_BAR;
;             G_LDB(B0, 1, 0); G_SCHED; G_LDA(At, 1, 0); G_STAGE(G_SA(0, 1), a2 + hstepA, voffA);
;             G_WAIT_L(8); G_BAR; G_WAIT_L(0); G_MMA(0, 0, At, B0); G_BAR; G_SCHED;
;             G_LDB(B1, 1, 1); G_STAGE(G_SB(1, 0), b3, voffB);
;             G_BAR; G_WAIT_L(0); G_MMA(0, 1, At, B1); G_BAR;
;             G_LDA(At, 1, 1); G_STAGE(G_SA(1, 0), a3, voffA);
;             G_BAR; G_WAIT_L(0); G_MMA(1, 0, At, B0); G_BAR; G_SCHED;
;             G_STAGE(G_SB(1, 1), b3 + hstepB, voffB);
;             G_WAIT_V(6); G_BAR; G_MMA(1, 1, At, B1); G_BAR;
; DI float row_rstd(const unsigned char* ws, int row, int which, int fq) {
;     const f32x4 s4 = *(const f32x4*)((const float*)(ws + WS_SSQ) + (size_t)row * 32 + which * 16 + fq * 4);
;     float ss = s4[0] + s4[1] + s4[2] + s4[3];
;     ss += __shfl_xor(ss, 16); ss += __shfl_xor(ss, 32);
;     return rsqrtf(ss * (1.f / 512.f) + 1e-6f);
; }
;     DI void operator()(const f32x4 (&acc)[2][2][4][2], const Unit& u, int wr, int wc, int fr, int fq) const {
;     ...
;                 const int row = u.pm * BM + ai * HALF + wr * 64 + m * 16 + fr;
;                 const int r = row - b * RB;
;                 const float rs = row_rstd(ws, row, 1, fq);
;                 {
;                     const f32x4 v0 = acc[ai][0][m][0] * rs, v1 = acc[ai][0][m][1] * rs;
;                     bf16_t* kp = Km + (size_t)row * 640 + head * 128 + wc * 32 + 4 * fq;
;                     st_bf16x4(kp, v0); st_bf16x4(kp + 16, v1);
	s_waitcnt lgkmcnt(0)
	s_setprio 1
	s_waitcnt lgkmcnt(0)
	v_mfma_f32_16x16x32_bf16 v[60:63], v[150:153], v[176:179], v[60:63]
	v_mfma_f32_16x16x32_bf16 v[56:59], v[168:171], v[176:179], v[56:59]
	v_mfma_f32_16x16x32_bf16 v[44:47], v[150:153], v[184:187], v[44:47]
	v_mfma_f32_16x16x32_bf16 v[40:43], v[168:171], v[184:187], v[40:43]
	v_mfma_f32_16x16x32_bf16 v[28:31], v[150:153], v[192:195], v[28:31]
	v_mfma_f32_16x16x32_bf16 v[24:27], v[168:171], v[192:195], v[24:27]
	v_mfma_f32_16x16x32_bf16 v[12:15], v[150:153], v[204:207], v[12:15]
	v_mfma_f32_16x16x32_bf16 v[8:11], v[168:171], v[204:207], v[8:11]
	v_mfma_f32_16x16x32_bf16 v[60:63], v[164:167], v[180:183], v[60:63]
	v_mfma_f32_16x16x32_bf16 v[56:59], v[172:175], v[180:183], v[56:59]
	v_mfma_f32_16x16x32_bf16 v[44:47], v[164:167], v[188:191], v[44:47]
	v_mfma_f32_16x16x32_bf16 v[40:43], v[172:175], v[188:191], v[40:43]
	v_mfma_f32_16x16x32_bf16 v[28:31], v[164:167], v[196:199], v[28:31]
	v_mfma_f32_16x16x32_bf16 v[24:27], v[172:175], v[196:199], v[24:27]
	v_mfma_f32_16x16x32_bf16 v[12:15], v[164:167], v[208:211], v[12:15]
	v_mfma_f32_16x16x32_bf16 v[8:11], v[172:175], v[208:211], v[8:11]
	s_setprio 0
	s_barrier
	s_add_u32 s8, s8, 0x20080
	s_addc_u32 s9, s9, 0
	s_add_i32 s20, s20, s31
	v_lshl_add_u64 v[150:151], s[8:9], 0, v[130:131]
	s_mov_b32 m0, s20
	s_nop 0
	global_load_lds_dwordx4 v[150:151], off
	v_lshl_add_u64 v[150:151], s[8:9], 0, v[134:135]
	s_add_i32 m0, s20, 0x2000
	s_nop 0
	global_load_lds_dwordx4 v[150:151], off
	s_waitcnt vmcnt(6)
	s_barrier
	s_setprio 1
	v_mfma_f32_16x16x32_bf16 v[52:55], v[212:215], v[176:179], v[52:55]
	v_mfma_f32_16x16x32_bf16 v[48:51], v[220:223], v[176:179], v[48:51]
	v_mfma_f32_16x16x32_bf16 v[36:39], v[212:215], v[184:187], v[36:39]
	v_mfma_f32_16x16x32_bf16 v[32:35], v[220:223], v[184:187], v[32:35]
	v_mfma_f32_16x16x32_bf16 v[20:23], v[212:215], v[192:195], v[20:23]
	v_mfma_f32_16x16x32_bf16 v[16:19], v[220:223], v[192:195], v[16:19]
	v_mfma_f32_16x16x32_bf16 v[4:7], v[212:215], v[204:207], v[4:7]
	v_mfma_f32_16x16x32_bf16 v[0:3], v[220:223], v[204:207], v[0:3]
	v_mfma_f32_16x16x32_bf16 v[52:55], v[216:219], v[180:183], v[52:55]
	v_mfma_f32_16x16x32_bf16 v[48:51], v[224:227], v[180:183], v[48:51]
	v_mfma_f32_16x16x32_bf16 v[36:39], v[216:219], v[188:191], v[36:39]
	v_mfma_f32_16x16x32_bf16 v[32:35], v[224:227], v[188:191], v[32:35]
	v_mfma_f32_16x16x32_bf16 v[20:23], v[216:219], v[196:199], v[20:23]
	v_mfma_f32_16x16x32_bf16 v[16:19], v[224:227], v[196:199], v[16:19]
	v_mfma_f32_16x16x32_bf16 v[4:7], v[216:219], v[208:211], v[4:7]
	v_mfma_f32_16x16x32_bf16 v[0:3], v[224:227], v[208:211], v[0:3]
	s_setprio 0
	s_add_i32 s28, s28, 2
	s_add_u32 s82, s82, 0x100
	s_addc_u32 s83, s83, 0
	s_cmp_gt_u32 s28, 5
	s_mov_b64 s[20:21], s[0:1]
	s_barrier
	s_cbranch_scc0 .LBB0_1071
	v_lshl_add_u32 v154, s79, 8, v141
	v_ashrrev_i32_e32 v155, 31, v154
	v_lshlrev_b64 v[150:151], 7, v[154:155]
	v_lshl_add_u64 v[150:151], s[52:53], 0, v[150:151]
	v_lshl_add_u64 v[150:151], v[150:151], 0, v[136:137]
	v_add_co_u32_e32 v150, vcc, s69, v150
	s_mul_hi_i32 s1, s79, 0x38e38e39
	s_nop 0
	v_addc_co_u32_e32 v151, vcc, 0, v151, vcc
	global_load_dwordx4 v[164:167], v[150:151], off offset:64
	s_mov_b64 s[98:99], 0x800
	v_lshl_add_u64 v[232:233], s[98:99], 0, v[150:151]
	global_load_dwordx4 v[232:235], v[232:233], off offset:64
	s_mov_b64 s[98:99], 0x1000
	v_lshl_add_u64 v[236:237], s[98:99], 0, v[150:151]
	global_load_dwordx4 v[236:239], v[236:237], off offset:64
	s_mov_b64 s[98:99], 0x1800
	v_lshl_add_u64 v[240:241], s[98:99], 0, v[150:151]
	global_load_dwordx4 v[240:243], v[240:241], off offset:64
	s_mov_b64 s[98:99], 0x4000
	v_lshl_add_u64 v[244:245], s[98:99], 0, v[150:151]
	global_load_dwordx4 v[244:247], v[244:245], off offset:64
	s_mov_b64 s[98:99], 0x4800
	v_lshl_add_u64 v[248:249], s[98:99], 0, v[150:151]
	global_load_dwordx4 v[248:251], v[248:249], off offset:64
	v_and_b32_e32 v151, 64, v160
	v_xor_b32_e32 v150, 16, v160
	v_add_u32_e32 v151, 64, v151
	v_cmp_lt_i32_e32 vcc, v150, v151
	s_lshl_b32 s0, s80, 7
	s_lshr_b32 s8, s1, 31
	v_cndmask_b32_e32 v163, v160, v150, vcc
	s_ashr_i32 s9, s1, 1
	s_ashr_i32 s1, s0, 31
	v_lshlrev_b32_e32 v163, 2, v163
	v_xor_b32_e32 v155, 32, v160
	v_or_b32_e32 v168, s0, v140
	s_add_i32 s9, s9, s8
	v_mov_b32_e32 v169, s1
	v_mov_b64_e32 v[152:153], s[12:13]
	v_cmp_lt_i32_e32 vcc, v155, v151
	v_lshl_add_u64 v[150:151], s[0:1], 1, v[138:139]
	s_mul_i32 s8, s9, 0xfffff700
	v_mad_i64_i32 v[168:169], s[0:1], s9, v162, v[168:169]
	v_add_u32_e32 v172, s8, v154
	v_mad_u64_u32 v[152:153], s[0:1], v168, s72, v[152:153]
	v_mad_i32_i24 v153, v169, s72, v153
	v_ashrrev_i32_e32 v173, 31, v172
	v_cndmask_b32_e32 v155, v160, v155, vcc
	v_lshl_add_u64 v[168:169], v[172:173], 1, v[152:153]
	v_lshlrev_b32_e32 v155, 2, v155
	v_add_co_u32_e32 v172, vcc, s54, v168
	v_mad_i64_i32 v[170:171], s[0:1], v154, s71, v[150:151]
	s_nop 0
	v_addc_co_u32_e32 v173, vcc, 0, v169, vcc
	v_add_co_u32_e32 v174, vcc, s74, v168
	s_mov_b32 s80, s14
	s_nop 0
	v_addc_co_u32_e32 v175, vcc, 0, v169, vcc
	s_mov_b32 s79, s78
	s_mov_b64 s[22:23], s[18:19]
	s_mov_b64 s[20:21], s[16:17]
	s_waitcnt vmcnt(5) lgkmcnt(0)
	v_add_f32_e32 v164, v164, v165
	v_add_f32_e32 v164, v166, v164
	v_add_f32_e32 v166, v167, v164
	ds_bpermute_b32 v167, v163, v166
	v_add_co_u32_e32 v164, vcc, s75, v168
	s_waitcnt lgkmcnt(0)
	v_add_f32_e32 v176, v166, v167
	ds_bpermute_b32 v177, v155, v176
	v_addc_co_u32_e32 v165, vcc, 0, v169, vcc
	v_add_co_u32_e32 v166, vcc, s42, v168
	s_waitcnt lgkmcnt(0)
; DI bf16_t f2bf(float x) { unsigned u = __float_as_uint(x); u += 0x7fffu + ((u >> 16) & 1u); return (bf16_t)(u >> 16); }
; DI void st_bf16x4(bf16_t* p, f32x4 v) { u32x2 w; w.x = cvt_pk_bf16(v[0], v[1]); w.y = cvt_pk_bf16(v[2], v[3]); *(u32x2*)p = w; }
; DI float row_rstd(const unsigned char* ws, int row, int which, int fq) {
;     const f32x4 s4 = *(const f32x4*)((const float*)(ws + WS_SSQ) + (size_t)row * 32 + which * 16 + fq * 4);
;     float ss = s4[0] + s4[1] + s4[2] + s4[3];
;     ss += __shfl_xor(ss, 16); ss += __shfl_xor(ss, 32);
;     return rsqrtf(ss * (1.f / 512.f) + 1e-6f);
; }
;     DI void operator()(const f32x4 (&acc)[2][2][4][2], const Unit& u, int wr, int wc, int fr, int fq) const {
;         bf16_t* Km = (bf16_t*)(ws + WS_KM);
;         const int b = u.pm / 9, head = u.pn;
; #pragma unroll
;         for (int ai = 0; ai < 2; ++ai)
; #pragma unroll
;             for (int m = 0; m < 4; ++m) {
;                 const int row = u.pm * BM + ai * HALF + wr * 64 + m * 16 + fr;
;                 const int r = row - b * RB;
;                 const float rs = row_rstd(ws, row, 1, fq);
;                 {
;                     const f32x4 v0 = acc[ai][0][m][0] * rs, v1 = acc[ai][0][m][1] * rs;
;                     bf16_t* kp = Km + (size_t)row * 640 + head * 128 + wc * 32 + 4 * fq;
;                     st_bf16x4(kp, v0); st_bf16x4(kp + 16, v1);
;                 }
;                 {
;                     const f32x4 v0 = acc[ai][1][m][0] * rs, v1 = acc[ai][1][m][1] * rs;
;                     bf16_t* vt = (bf16_t*)(ws + WS_VTM) + ((size_t)b * 640 + head * 128 + wc * 32 + 4 * fq) * RB + r;
; #pragma unroll
;                     for (int j = 0; j < 4; ++j) { vt[(size_t)j * RB] = f2bf(v0[j]); vt[(size_t)(16 + j) * RB] = f2bf(v1[j]); }
;                 }
;             }
;     }
	v_add_f32_e32 v176, v176, v177
	v_addc_co_u32_e32 v167, vcc, 0, v169, vcc
	v_fmamk_f32 v176, v176, 0x3b000000, v161
	v_mul_f32_e32 v177, 0x4b800000, v176
	v_cmp_gt_f32_e32 vcc, s70, v176
	s_nop 1
	v_cndmask_b32_e32 v176, v176, v177, vcc
	v_rsq_f32_e32 v178, v176
	v_add_co_u32_e64 v176, s[0:1], s55, v168
	v_mul_f32_e32 v179, 0x45800000, v178
	v_cndmask_b32_e32 v178, v178, v179, vcc
	v_pk_mul_f32 v[126:127], v[126:127], v[178:179] op_sel_hi:[1,0]
	v_pk_mul_f32 v[124:125], v[124:125], v[178:179] op_sel_hi:[1,0]
	v_pk_mul_f32 v[122:123], v[122:123], v[178:179] op_sel_hi:[1,0]
	v_pk_mul_f32 v[120:121], v[120:121], v[178:179] op_sel_hi:[1,0]
	v_mul_f32_e32 v116, v116, v178
	v_mul_f32_e32 v179, v112, v178
	v_mul_f32_e32 v117, v117, v178
	v_mul_f32_e32 v180, v113, v178
	v_mul_f32_e32 v118, v118, v178
	v_mul_f32_e32 v114, v114, v178
	v_cvt_pk_bf16_f32 v112, v124, v125
	v_cvt_pk_bf16_f32 v113, v126, v127
	v_mul_f32_e32 v119, v119, v178
	v_bfe_u32 v124, v116, 16, 1
	v_bfe_u32 v125, v179, 16, 1
	v_bfe_u32 v126, v117, 16, 1
	v_bfe_u32 v127, v180, 16, 1
	v_bfe_u32 v181, v118, 16, 1
	v_bfe_u32 v182, v114, 16, 1
	global_store_dwordx2 v[170:171], v[112:113], off
	v_cvt_pk_bf16_f32 v112, v120, v121
	v_cvt_pk_bf16_f32 v113, v122, v123
	v_addc_co_u32_e64 v177, s[0:1], 0, v169, s[0:1]
	v_bfe_u32 v183, v119, 16, 1
	v_add3_u32 v116, v116, v124, s73
	v_add3_u32 v120, v179, v125, s73
	v_add3_u32 v117, v117, v126, s73
	v_add3_u32 v121, v180, v127, s73
	v_add3_u32 v118, v118, v181, s73
	v_add3_u32 v114, v114, v182, s73
	global_store_dwordx2 v[170:171], v[112:113], off offset:32
	global_store_short_d16_hi v[168:169], v116, off
	global_store_short_d16_hi v[172:173], v120, off
	global_store_short_d16_hi v[174:175], v117, off offset:512
	global_store_short_d16_hi v[164:165], v121, off offset:512
	global_store_short_d16_hi v[166:167], v118, off offset:1024
	global_store_short_d16_hi v[176:177], v114, off offset:1024
	v_add_co_u32_e32 v112, vcc, s76, v168
	v_add3_u32 v119, v119, v183, s73
	s_nop 0
	v_addc_co_u32_e32 v113, vcc, 0, v169, vcc
	global_store_short_d16_hi v[112:113], v119, off offset:1536
	v_mul_f32_e32 v112, v115, v178
	v_bfe_u32 v113, v112, 16, 1
	v_add3_u32 v114, v112, v113, s73
	v_add_co_u32_e32 v112, vcc, s77, v168
	v_or_b32_e32 v116, 16, v154
	s_nop 0
	v_addc_co_u32_e32 v113, vcc, 0, v169, vcc
	v_ashrrev_i32_e32 v117, 31, v116
	global_store_short_d16_hi v[112:113], v114, off offset:1536
	v_lshlrev_b64 v[112:113], 7, v[116:117]
	v_lshl_add_u64 v[112:113], s[52:53], 0, v[112:113]
	v_lshl_add_u64 v[112:113], v[112:113], 0, v[136:137]
	v_add_co_u32_e32 v112, vcc, s69, v112
	v_mad_i64_i32 v[118:119], s[0:1], v116, s71, v[150:151]
	s_nop 0
	v_addc_co_u32_e32 v113, vcc, 0, v113, vcc
	v_add_u32_e32 v116, s8, v116
	v_ashrrev_i32_e32 v117, 31, v116
	v_lshl_add_u64 v[116:117], v[116:117], 1, v[152:153]
	v_add_co_u32_e32 v120, vcc, s54, v116
	s_waitcnt vmcnt(14) lgkmcnt(0)
	v_mov_b32_e32 v112, v232
	v_mov_b32_e32 v113, v233
	v_mov_b32_e32 v114, v234
	v_mov_b32_e32 v115, v235
	v_add_f32_e32 v112, v112, v113
	v_add_f32_e32 v112, v114, v112
	v_add_f32_e32 v114, v115, v112
	ds_bpermute_b32 v115, v163, v114
	v_addc_co_u32_e32 v121, vcc, 0, v117, vcc
	v_add_co_u32_e32 v122, vcc, s74, v116
	s_waitcnt lgkmcnt(0)
	v_add_f32_e32 v126, v114, v115
	v_addc_co_u32_e32 v123, vcc, 0, v117, vcc
	ds_bpermute_b32 v127, v155, v126
	v_add_co_u32_e32 v124, vcc, s75, v116
	s_waitcnt lgkmcnt(0)
	v_add_f32_e32 v126, v126, v127
	v_addc_co_u32_e32 v125, vcc, 0, v117, vcc
	v_add_co_u32_e32 v112, vcc, s42, v116
	v_fmamk_f32 v126, v126, 0x3b000000, v161
	s_nop 0
	v_addc_co_u32_e32 v113, vcc, 0, v117, vcc
	v_add_co_u32_e32 v114, vcc, s55, v116
	v_mul_f32_e32 v127, 0x4b800000, v126
	s_nop 0
	v_addc_co_u32_e32 v115, vcc, 0, v117, vcc
	v_cmp_gt_f32_e32 vcc, s70, v126
	s_nop 1
	v_cndmask_b32_e32 v126, v126, v127, vcc
	v_rsq_f32_e32 v164, v126
	v_add_co_u32_e64 v126, s[0:1], s76, v116
	v_mul_f32_e32 v165, 0x45800000, v164
	v_cndmask_b32_e32 v164, v164, v165, vcc
	v_pk_mul_f32 v[108:109], v[108:109], v[164:165] op_sel_hi:[1,0]
	v_mul_f32_e32 v100, v100, v164
	v_pk_mul_f32 v[110:111], v[110:111], v[164:165] op_sel_hi:[1,0]
	v_pk_mul_f32 v[106:107], v[106:107], v[164:165] op_sel_hi:[1,0]
	v_pk_mul_f32 v[104:105], v[104:105], v[164:165] op_sel_hi:[1,0]
	v_mul_f32_e32 v165, v96, v164
	v_mul_f32_e32 v101, v101, v164
	v_mul_f32_e32 v166, v97, v164
	v_mul_f32_e32 v102, v102, v164
	v_mul_f32_e32 v98, v98, v164
	v_mul_f32_e32 v103, v103, v164
	v_cvt_pk_bf16_f32 v96, v108, v109
	v_cvt_pk_bf16_f32 v97, v110, v111
	v_bfe_u32 v108, v100, 16, 1
	v_mul_f32_e32 v99, v99, v164
	v_bfe_u32 v109, v165, 16, 1
	v_bfe_u32 v110, v101, 16, 1
	v_bfe_u32 v111, v166, 16, 1
	v_bfe_u32 v164, v102, 16, 1
	v_bfe_u32 v167, v98, 16, 1
	v_bfe_u32 v168, v103, 16, 1
	global_store_dwordx2 v[118:119], v[96:97], off
	v_cvt_pk_bf16_f32 v96, v104, v105
	v_cvt_pk_bf16_f32 v97, v106, v107
	v_add3_u32 v100, v100, v108, s73
	v_addc_co_u32_e64 v127, s[0:1], 0, v117, s[0:1]
	v_bfe_u32 v169, v99, 16, 1
	v_add3_u32 v104, v165, v109, s73
	v_add3_u32 v101, v101, v110, s73
	v_add3_u32 v105, v166, v111, s73
	v_add3_u32 v102, v102, v164, s73
	v_add3_u32 v98, v98, v167, s73
	v_add3_u32 v103, v103, v168, s73
	global_store_dwordx2 v[118:119], v[96:97], off offset:32
	global_store_short_d16_hi v[116:117], v100, off
	global_store_short_d16_hi v[120:121], v104, off
	global_store_short_d16_hi v[122:123], v101, off offset:512
	global_store_short_d16_hi v[124:125], v105, off offset:512
	global_store_short_d16_hi v[112:113], v102, off offset:1024
	global_store_short_d16_hi v[114:115], v98, off offset:1024
	global_store_short_d16_hi v[126:127], v103, off offset:1536
	v_add_co_u32_e32 v96, vcc, s77, v116
	v_or_b32_e32 v100, 32, v154
	v_add3_u32 v99, v99, v169, s73
	v_addc_co_u32_e32 v97, vcc, 0, v117, vcc
	v_ashrrev_i32_e32 v101, 31, v100
	global_store_short_d16_hi v[96:97], v99, off offset:1536
	v_lshlrev_b64 v[96:97], 7, v[100:101]
	v_lshl_add_u64 v[96:97], s[52:53], 0, v[96:97]
	v_lshl_add_u64 v[96:97], v[96:97], 0, v[136:137]
	v_add_co_u32_e32 v96, vcc, s69, v96
	v_mad_i64_i32 v[104:105], s[0:1], v100, s71, v[150:151]
	s_nop 0
	v_addc_co_u32_e32 v97, vcc, 0, v97, vcc
	s_mov_b64 s[98:99], 0x4000
	v_lshl_add_u64 v[232:233], s[98:99], 0, v[96:97]
	global_load_dwordx4 v[232:235], v[232:233], off offset:64
	v_add_u32_e32 v100, s8, v100
	v_ashrrev_i32_e32 v101, 31, v100
	v_lshl_add_u64 v[100:101], v[100:101], 1, v[152:153]
	v_add_co_u32_e32 v108, vcc, s54, v100
	v_or_b32_e32 v102, 48, v154
	s_nop 0
	v_addc_co_u32_e32 v109, vcc, 0, v101, vcc
	v_add_co_u32_e32 v110, vcc, s74, v100
	v_ashrrev_i32_e32 v103, 31, v102
	s_nop 0
	v_addc_co_u32_e32 v111, vcc, 0, v101, vcc
	v_lshlrev_b64 v[106:107], 7, v[102:103]
	v_add_co_u32_e32 v112, vcc, s75, v100
	v_lshl_add_u64 v[106:107], s[52:53], 0, v[106:107]
	s_nop 0
	v_addc_co_u32_e32 v113, vcc, 0, v101, vcc
	v_add_co_u32_e32 v114, vcc, s42, v100
	v_lshl_add_u64 v[106:107], v[106:107], 0, v[136:137]
	s_nop 0
	v_addc_co_u32_e32 v115, vcc, 0, v101, vcc
	s_waitcnt vmcnt(24) lgkmcnt(0)
; DI bf16_t f2bf(float x) { unsigned u = __float_as_uint(x); u += 0x7fffu + ((u >> 16) & 1u); return (bf16_t)(u >> 16); }
; DI void st_bf16x4(bf16_t* p, f32x4 v) { u32x2 w; w.x = cvt_pk_bf16(v[0], v[1]); w.y = cvt_pk_bf16(v[2], v[3]); *(u32x2*)p = w; }
; DI float row_rstd(const unsigned char* ws, int row, int which, int fq) {
;     const f32x4 s4 = *(const f32x4*)((const float*)(ws + WS_SSQ) + (size_t)row * 32 + which * 16 + fq * 4);
;     float ss = s4[0] + s4[1] + s4[2] + s4[3];
;     ss += __shfl_xor(ss, 16); ss += __shfl_xor(ss, 32);
;     return rsqrtf(ss * (1.f / 512.f) + 1e-6f);
; }
;     DI void operator()(const f32x4 (&acc)[2][2][4][2], const Unit& u, int wr, int wc, int fr, int fq) const {
;         bf16_t* Km = (bf16_t*)(ws + WS_KM);
;         const int b = u.pm / 9, head = u.pn;
; #pragma unroll
;         for (int ai = 0; ai < 2; ++ai)
; #pragma unroll
;             for (int m = 0; m < 4; ++m) {
;                 const int row = u.pm * BM + ai * HALF + wr * 64 + m * 16 + fr;
;                 const int r = row - b * RB;
;                 const float rs = row_rstd(ws, row, 1, fq);
;                 {
;                     const f32x4 v0 = acc[ai][0][m][0] * rs, v1 = acc[ai][0][m][1] * rs;
;                     bf16_t* kp = Km + (size_t)row * 640 + head * 128 + wc * 32 + 4 * fq;
;                     st_bf16x4(kp, v0); st_bf16x4(kp + 16, v1);
;                 }
;                 {
;                     const f32x4 v0 = acc[ai][1][m][0] * rs, v1 = acc[ai][1][m][1] * rs;
;                     bf16_t* vt = (bf16_t*)(ws + WS_VTM) + ((size_t)b * 640 + head * 128 + wc * 32 + 4 * fq) * RB + r;
; #pragma unroll
;                     for (int j = 0; j < 4; ++j) { vt[(size_t)j * RB] = f2bf(v0[j]); vt[(size_t)(16 + j) * RB] = f2bf(v1[j]); }
;                 }
;             }
;     }
	v_mov_b32_e32 v96, v236
	v_mov_b32_e32 v97, v237
	v_mov_b32_e32 v98, v238
	v_mov_b32_e32 v99, v239
	v_add_f32_e32 v96, v96, v97
	v_add_f32_e32 v96, v98, v96
	v_add_f32_e32 v98, v99, v96
	ds_bpermute_b32 v99, v163, v98
	v_add_co_u32_e32 v96, vcc, s55, v100
	s_waitcnt lgkmcnt(0)
	v_add_f32_e32 v103, v98, v99
	ds_bpermute_b32 v116, v155, v103
	v_addc_co_u32_e32 v97, vcc, 0, v101, vcc
	v_add_co_u32_e32 v98, vcc, s76, v100
	s_waitcnt lgkmcnt(0)
	v_add_f32_e32 v103, v103, v116
	v_addc_co_u32_e32 v99, vcc, 0, v101, vcc
	v_fmamk_f32 v103, v103, 0x3b000000, v161
	v_mul_f32_e32 v116, 0x4b800000, v103
	v_cmp_gt_f32_e32 vcc, s70, v103
	s_nop 1
	v_cndmask_b32_e32 v103, v103, v116, vcc
	v_rsq_f32_e32 v103, v103
	v_add_co_u32_e64 v116, s[0:1], s77, v100
	v_mul_f32_e32 v118, 0x45800000, v103
	v_cndmask_b32_e32 v118, v103, v118, vcc
	v_pk_mul_f32 v[94:95], v[94:95], v[118:119] op_sel_hi:[1,0]
	v_pk_mul_f32 v[92:93], v[92:93], v[118:119] op_sel_hi:[1,0]
	v_pk_mul_f32 v[90:91], v[90:91], v[118:119] op_sel_hi:[1,0]
	v_pk_mul_f32 v[88:89], v[88:89], v[118:119] op_sel_hi:[1,0]
	v_mul_f32_e32 v84, v84, v118
	v_mul_f32_e32 v103, v80, v118
	v_mul_f32_e32 v85, v85, v118
	v_mul_f32_e32 v119, v81, v118
	v_mul_f32_e32 v86, v86, v118
	v_mul_f32_e32 v82, v82, v118
	v_mul_f32_e32 v87, v87, v118
	v_mul_f32_e32 v83, v83, v118
	v_cvt_pk_bf16_f32 v80, v92, v93
	v_cvt_pk_bf16_f32 v81, v94, v95
	v_bfe_u32 v92, v84, 16, 1
	v_bfe_u32 v93, v103, 16, 1
	v_bfe_u32 v94, v85, 16, 1
	v_bfe_u32 v95, v119, 16, 1
	v_bfe_u32 v118, v86, 16, 1
	v_bfe_u32 v120, v82, 16, 1
	v_bfe_u32 v121, v87, 16, 1
	v_bfe_u32 v122, v83, 16, 1
	global_store_dwordx2 v[104:105], v[80:81], off
	v_cvt_pk_bf16_f32 v80, v88, v89
	v_cvt_pk_bf16_f32 v81, v90, v91
	v_addc_co_u32_e64 v117, s[0:1], 0, v101, s[0:1]
	v_add3_u32 v84, v84, v92, s73
	v_add3_u32 v88, v103, v93, s73
	v_add3_u32 v85, v85, v94, s73
	v_add3_u32 v89, v119, v95, s73
	v_add3_u32 v86, v86, v118, s73
	v_add3_u32 v82, v82, v120, s73
	v_add3_u32 v87, v87, v121, s73
	v_add3_u32 v83, v83, v122, s73
	global_store_dwordx2 v[104:105], v[80:81], off offset:32
	global_store_short_d16_hi v[100:101], v84, off
	global_store_short_d16_hi v[108:109], v88, off
	global_store_short_d16_hi v[110:111], v85, off offset:512
	global_store_short_d16_hi v[112:113], v89, off offset:512
	global_store_short_d16_hi v[114:115], v86, off offset:1024
	global_store_short_d16_hi v[96:97], v82, off offset:1024
	global_store_short_d16_hi v[98:99], v87, off offset:1536
	global_store_short_d16_hi v[116:117], v83, off offset:1536
	v_add_co_u32_e32 v80, vcc, s69, v106
	v_add_u32_e32 v84, 0x80, v154
	s_nop 0
	v_addc_co_u32_e32 v81, vcc, 0, v107, vcc
	s_mov_b64 s[98:99], 0x4000
	v_lshl_add_u64 v[236:237], s[98:99], 0, v[80:81]
	global_load_dwordx4 v[236:239], v[236:237], off offset:64
	v_ashrrev_i32_e32 v85, 31, v84
	v_lshlrev_b64 v[88:89], 7, v[84:85]
	v_lshl_add_u64 v[88:89], s[52:53], 0, v[88:89]
	v_add_u32_e32 v90, s8, v102
	v_lshl_add_u64 v[88:89], v[88:89], 0, v[136:137]
	v_ashrrev_i32_e32 v91, 31, v90
	v_add_co_u32_e32 v88, vcc, s69, v88
	v_lshl_add_u64 v[90:91], v[90:91], 1, v[152:153]
	s_nop 0
	v_addc_co_u32_e32 v89, vcc, 0, v89, vcc
	v_add_co_u32_e32 v92, vcc, s54, v90
	v_mad_i64_i32 v[86:87], s[0:1], v102, s71, v[150:151]
	s_nop 0
	v_addc_co_u32_e32 v93, vcc, 0, v91, vcc
	v_add_co_u32_e32 v94, vcc, s74, v90
	s_waitcnt vmcnt(34) lgkmcnt(0)
	v_mov_b32_e32 v80, v240
	v_mov_b32_e32 v81, v241
	v_mov_b32_e32 v82, v242
	v_mov_b32_e32 v83, v243
	v_add_f32_e32 v80, v80, v81
	v_add_f32_e32 v80, v82, v80
	v_add_f32_e32 v82, v83, v80
	ds_bpermute_b32 v83, v163, v82
	v_addc_co_u32_e32 v95, vcc, 0, v91, vcc
	v_add_co_u32_e32 v96, vcc, s75, v90
	s_waitcnt lgkmcnt(0)
	v_add_f32_e32 v85, v82, v83
	v_addc_co_u32_e32 v97, vcc, 0, v91, vcc
	ds_bpermute_b32 v100, v155, v85
	v_add_co_u32_e32 v98, vcc, s42, v90
	s_waitcnt lgkmcnt(0)
	v_add_f32_e32 v85, v85, v100
	v_addc_co_u32_e32 v99, vcc, 0, v91, vcc
	v_add_co_u32_e32 v80, vcc, s55, v90
	v_fmamk_f32 v85, v85, 0x3b000000, v161
	s_nop 0
	v_addc_co_u32_e32 v81, vcc, 0, v91, vcc
	v_add_co_u32_e32 v82, vcc, s76, v90
	v_mul_f32_e32 v100, 0x4b800000, v85
	s_nop 0
	v_addc_co_u32_e32 v83, vcc, 0, v91, vcc
	v_cmp_gt_f32_e32 vcc, s70, v85
	s_nop 1
	v_cndmask_b32_e32 v85, v85, v100, vcc
	v_rsq_f32_e32 v85, v85
	v_add_co_u32_e64 v100, s[0:1], s77, v90
	v_mul_f32_e32 v102, 0x45800000, v85
	v_cndmask_b32_e32 v102, v85, v102, vcc
	v_pk_mul_f32 v[78:79], v[78:79], v[102:103] op_sel_hi:[1,0]
	v_pk_mul_f32 v[76:77], v[76:77], v[102:103] op_sel_hi:[1,0]
	v_pk_mul_f32 v[74:75], v[74:75], v[102:103] op_sel_hi:[1,0]
	v_pk_mul_f32 v[72:73], v[72:73], v[102:103] op_sel_hi:[1,0]
	v_mul_f32_e32 v68, v68, v102
	v_mul_f32_e32 v85, v64, v102
	v_mul_f32_e32 v69, v69, v102
	v_mul_f32_e32 v103, v65, v102
	v_mul_f32_e32 v70, v70, v102
	v_mul_f32_e32 v66, v66, v102
	v_mul_f32_e32 v71, v71, v102
	v_mul_f32_e32 v67, v67, v102
	v_cvt_pk_bf16_f32 v64, v76, v77
	v_cvt_pk_bf16_f32 v65, v78, v79
	v_bfe_u32 v76, v68, 16, 1
	v_bfe_u32 v77, v85, 16, 1
	v_bfe_u32 v78, v69, 16, 1
	v_bfe_u32 v79, v103, 16, 1
	v_bfe_u32 v102, v70, 16, 1
	v_bfe_u32 v104, v66, 16, 1
	v_bfe_u32 v105, v71, 16, 1
	v_bfe_u32 v106, v67, 16, 1
	global_store_dwordx2 v[86:87], v[64:65], off
	v_cvt_pk_bf16_f32 v64, v72, v73
	v_cvt_pk_bf16_f32 v65, v74, v75
	v_addc_co_u32_e64 v101, s[0:1], 0, v91, s[0:1]
	v_add3_u32 v68, v68, v76, s73
	v_add3_u32 v72, v85, v77, s73
	v_add3_u32 v69, v69, v78, s73
	v_add3_u32 v73, v103, v79, s73
	v_add3_u32 v70, v70, v102, s73
	v_add3_u32 v66, v66, v104, s73
	v_add3_u32 v71, v71, v105, s73
	v_add3_u32 v67, v67, v106, s73
	global_store_dwordx2 v[86:87], v[64:65], off offset:32
	global_store_short_d16_hi v[90:91], v68, off
	global_store_short_d16_hi v[92:93], v72, off
	global_store_short_d16_hi v[94:95], v69, off offset:512
	global_store_short_d16_hi v[96:97], v73, off offset:512
	global_store_short_d16_hi v[98:99], v70, off offset:1024
	global_store_short_d16_hi v[80:81], v66, off offset:1024
	global_store_short_d16_hi v[82:83], v71, off offset:1536
	global_store_short_d16_hi v[100:101], v67, off offset:1536
	v_add_u32_e32 v68, 0x90, v154
	v_ashrrev_i32_e32 v69, 31, v68
	v_lshlrev_b64 v[72:73], 7, v[68:69]
	v_lshl_add_u64 v[72:73], s[52:53], 0, v[72:73]
	v_add_u32_e32 v74, s8, v84
	v_lshl_add_u64 v[72:73], v[72:73], 0, v[136:137]
	v_ashrrev_i32_e32 v75, 31, v74
	v_add_co_u32_e32 v72, vcc, s69, v72
	v_lshl_add_u64 v[74:75], v[74:75], 1, v[152:153]
	s_nop 0
	v_addc_co_u32_e32 v73, vcc, 0, v73, vcc
	v_add_co_u32_e32 v76, vcc, s54, v74
	v_mad_i64_i32 v[70:71], s[0:1], v84, s71, v[150:151]
	s_nop 0
	v_addc_co_u32_e32 v77, vcc, 0, v75, vcc
	v_add_co_u32_e32 v78, vcc, s74, v74
	s_waitcnt vmcnt(43) lgkmcnt(0)
; DI bf16_t f2bf(float x) { unsigned u = __float_as_uint(x); u += 0x7fffu + ((u >> 16) & 1u); return (bf16_t)(u >> 16); }
; DI void st_bf16x4(bf16_t* p, f32x4 v) { u32x2 w; w.x = cvt_pk_bf16(v[0], v[1]); w.y = cvt_pk_bf16(v[2], v[3]); *(u32x2*)p = w; }
; DI float row_rstd(const unsigned char* ws, int row, int which, int fq) {
;     const f32x4 s4 = *(const f32x4*)((const float*)(ws + WS_SSQ) + (size_t)row * 32 + which * 16 + fq * 4);
;     float ss = s4[0] + s4[1] + s4[2] + s4[3];
;     ss += __shfl_xor(ss, 16); ss += __shfl_xor(ss, 32);
;     return rsqrtf(ss * (1.f / 512.f) + 1e-6f);
; }
;     DI void operator()(const f32x4 (&acc)[2][2][4][2], const Unit& u, int wr, int wc, int fr, int fq) const {
;         bf16_t* Km = (bf16_t*)(ws + WS_KM);
;         const int b = u.pm / 9, head = u.pn;
; #pragma unroll
;         for (int ai = 0; ai < 2; ++ai)
; #pragma unroll
;             for (int m = 0; m < 4; ++m) {
;                 const int row = u.pm * BM + ai * HALF + wr * 64 + m * 16 + fr;
;                 const int r = row - b * RB;
;                 const float rs = row_rstd(ws, row, 1, fq);
;                 {
;                     const f32x4 v0 = acc[ai][0][m][0] * rs, v1 = acc[ai][0][m][1] * rs;
;                     bf16_t* kp = Km + (size_t)row * 640 + head * 128 + wc * 32 + 4 * fq;
;                     st_bf16x4(kp, v0); st_bf16x4(kp + 16, v1);
;                 }
;                 {
;                     const f32x4 v0 = acc[ai][1][m][0] * rs, v1 = acc[ai][1][m][1] * rs;
;                     bf16_t* vt = (bf16_t*)(ws + WS_VTM) + ((size_t)b * 640 + head * 128 + wc * 32 + 4 * fq) * RB + r;
; #pragma unroll
;                     for (int j = 0; j < 4; ++j) { vt[(size_t)j * RB] = f2bf(v0[j]); vt[(size_t)(16 + j) * RB] = f2bf(v1[j]); }
;                 }
;             }
;     }
	v_mov_b32_e32 v64, v244
	v_mov_b32_e32 v65, v245
	v_mov_b32_e32 v66, v246
	v_mov_b32_e32 v67, v247
	v_add_f32_e32 v64, v64, v65
	v_add_f32_e32 v64, v66, v64
	v_add_f32_e32 v66, v67, v64
	ds_bpermute_b32 v67, v163, v66
	v_addc_co_u32_e32 v79, vcc, 0, v75, vcc
	v_add_co_u32_e32 v80, vcc, s75, v74
	s_waitcnt lgkmcnt(0)
	v_add_f32_e32 v69, v66, v67
	v_addc_co_u32_e32 v81, vcc, 0, v75, vcc
	ds_bpermute_b32 v84, v155, v69
	v_add_co_u32_e32 v82, vcc, s42, v74
	s_waitcnt lgkmcnt(0)
	v_add_f32_e32 v69, v69, v84
	v_addc_co_u32_e32 v83, vcc, 0, v75, vcc
	v_add_co_u32_e32 v64, vcc, s55, v74
	v_fmamk_f32 v69, v69, 0x3b000000, v161
	s_nop 0
	v_addc_co_u32_e32 v65, vcc, 0, v75, vcc
	v_add_co_u32_e32 v66, vcc, s76, v74
	v_mul_f32_e32 v84, 0x4b800000, v69
	s_nop 0
	v_addc_co_u32_e32 v67, vcc, 0, v75, vcc
	v_cmp_gt_f32_e32 vcc, s70, v69
	s_nop 1
	v_cndmask_b32_e32 v69, v69, v84, vcc
	v_rsq_f32_e32 v69, v69
	v_add_co_u32_e64 v84, s[0:1], s77, v74
	v_mul_f32_e32 v86, 0x45800000, v69
	v_cndmask_b32_e32 v86, v69, v86, vcc
	v_pk_mul_f32 v[62:63], v[62:63], v[86:87] op_sel_hi:[1,0]
	v_pk_mul_f32 v[60:61], v[60:61], v[86:87] op_sel_hi:[1,0]
	v_pk_mul_f32 v[58:59], v[58:59], v[86:87] op_sel_hi:[1,0]
	v_pk_mul_f32 v[56:57], v[56:57], v[86:87] op_sel_hi:[1,0]
	v_mul_f32_e32 v52, v52, v86
	v_mul_f32_e32 v69, v48, v86
	v_mul_f32_e32 v53, v53, v86
	v_mul_f32_e32 v87, v49, v86
	v_mul_f32_e32 v54, v54, v86
	v_mul_f32_e32 v50, v50, v86
	v_mul_f32_e32 v55, v55, v86
	v_mul_f32_e32 v51, v51, v86
	v_cvt_pk_bf16_f32 v48, v60, v61
	v_cvt_pk_bf16_f32 v49, v62, v63
	v_bfe_u32 v60, v52, 16, 1
	v_bfe_u32 v61, v69, 16, 1
	v_bfe_u32 v62, v53, 16, 1
	v_bfe_u32 v63, v87, 16, 1
	v_bfe_u32 v86, v54, 16, 1
	v_bfe_u32 v88, v50, 16, 1
	v_bfe_u32 v89, v55, 16, 1
	v_bfe_u32 v90, v51, 16, 1
	global_store_dwordx2 v[70:71], v[48:49], off
	v_cvt_pk_bf16_f32 v48, v56, v57
	v_cvt_pk_bf16_f32 v49, v58, v59
	v_addc_co_u32_e64 v85, s[0:1], 0, v75, s[0:1]
	v_add3_u32 v52, v52, v60, s73
	v_add3_u32 v56, v69, v61, s73
	v_add3_u32 v53, v53, v62, s73
	v_add3_u32 v57, v87, v63, s73
	v_add3_u32 v54, v54, v86, s73
	v_add3_u32 v50, v50, v88, s73
	v_add3_u32 v55, v55, v89, s73
	v_add3_u32 v51, v51, v90, s73
	global_store_dwordx2 v[70:71], v[48:49], off offset:32
	global_store_short_d16_hi v[74:75], v52, off
	global_store_short_d16_hi v[76:77], v56, off
	global_store_short_d16_hi v[78:79], v53, off offset:512
	global_store_short_d16_hi v[80:81], v57, off offset:512
	global_store_short_d16_hi v[82:83], v54, off offset:1024
	global_store_short_d16_hi v[64:65], v50, off offset:1024
	global_store_short_d16_hi v[66:67], v55, off offset:1536
	global_store_short_d16_hi v[84:85], v51, off offset:1536
	v_add_u32_e32 v52, 0xa0, v154
	v_ashrrev_i32_e32 v53, 31, v52
	v_lshlrev_b64 v[56:57], 7, v[52:53]
	v_lshl_add_u64 v[56:57], s[52:53], 0, v[56:57]
	v_add_u32_e32 v58, s8, v68
	v_lshl_add_u64 v[56:57], v[56:57], 0, v[136:137]
	v_ashrrev_i32_e32 v59, 31, v58
	v_add_co_u32_e32 v56, vcc, s69, v56
	v_lshl_add_u64 v[58:59], v[58:59], 1, v[152:153]
	s_nop 0
	v_addc_co_u32_e32 v57, vcc, 0, v57, vcc
	v_add_co_u32_e32 v60, vcc, s54, v58
	v_mad_i64_i32 v[54:55], s[0:1], v68, s71, v[150:151]
	s_nop 0
	v_addc_co_u32_e32 v61, vcc, 0, v59, vcc
	v_add_co_u32_e32 v62, vcc, s74, v58
	s_waitcnt vmcnt(52) lgkmcnt(0)
	v_mov_b32_e32 v48, v248
	v_mov_b32_e32 v49, v249
	v_mov_b32_e32 v50, v250
	v_mov_b32_e32 v51, v251
	v_add_f32_e32 v48, v48, v49
	v_add_f32_e32 v48, v50, v48
	v_add_f32_e32 v50, v51, v48
	ds_bpermute_b32 v51, v163, v50
	v_addc_co_u32_e32 v63, vcc, 0, v59, vcc
	v_add_co_u32_e32 v64, vcc, s75, v58
	s_waitcnt lgkmcnt(0)
	v_add_f32_e32 v53, v50, v51
	v_addc_co_u32_e32 v65, vcc, 0, v59, vcc
	ds_bpermute_b32 v68, v155, v53
	v_add_co_u32_e32 v66, vcc, s42, v58
	s_waitcnt lgkmcnt(0)
	v_add_f32_e32 v53, v53, v68
	v_addc_co_u32_e32 v67, vcc, 0, v59, vcc
	v_add_co_u32_e32 v48, vcc, s55, v58
	v_fmamk_f32 v53, v53, 0x3b000000, v161
	s_nop 0
	v_addc_co_u32_e32 v49, vcc, 0, v59, vcc
	v_add_co_u32_e32 v50, vcc, s76, v58
	v_mul_f32_e32 v68, 0x4b800000, v53
	s_nop 0
	v_addc_co_u32_e32 v51, vcc, 0, v59, vcc
	v_cmp_gt_f32_e32 vcc, s70, v53
	s_nop 1
	v_cndmask_b32_e32 v53, v53, v68, vcc
	v_rsq_f32_e32 v53, v53
	v_add_co_u32_e64 v68, s[0:1], s77, v58
	v_mul_f32_e32 v70, 0x45800000, v53
	v_cndmask_b32_e32 v70, v53, v70, vcc
	v_pk_mul_f32 v[46:47], v[46:47], v[70:71] op_sel_hi:[1,0]
	v_pk_mul_f32 v[44:45], v[44:45], v[70:71] op_sel_hi:[1,0]
	v_pk_mul_f32 v[42:43], v[42:43], v[70:71] op_sel_hi:[1,0]
	v_pk_mul_f32 v[40:41], v[40:41], v[70:71] op_sel_hi:[1,0]
	v_mul_f32_e32 v36, v36, v70
	v_mul_f32_e32 v53, v32, v70
	v_mul_f32_e32 v37, v37, v70
	v_mul_f32_e32 v71, v33, v70
	v_mul_f32_e32 v38, v38, v70
	v_mul_f32_e32 v34, v34, v70
	v_mul_f32_e32 v39, v39, v70
	v_mul_f32_e32 v35, v35, v70
	v_cvt_pk_bf16_f32 v32, v44, v45
	v_cvt_pk_bf16_f32 v33, v46, v47
	v_bfe_u32 v44, v36, 16, 1
	v_bfe_u32 v45, v53, 16, 1
	v_bfe_u32 v46, v37, 16, 1
	v_bfe_u32 v47, v71, 16, 1
	v_bfe_u32 v70, v38, 16, 1
	v_bfe_u32 v72, v34, 16, 1
	v_bfe_u32 v73, v39, 16, 1
	v_bfe_u32 v74, v35, 16, 1
	global_store_dwordx2 v[54:55], v[32:33], off
	v_cvt_pk_bf16_f32 v32, v40, v41
	v_cvt_pk_bf16_f32 v33, v42, v43
	v_addc_co_u32_e64 v69, s[0:1], 0, v59, s[0:1]
	v_add3_u32 v36, v36, v44, s73
	v_add3_u32 v40, v53, v45, s73
	v_add3_u32 v37, v37, v46, s73
	v_add3_u32 v41, v71, v47, s73
	v_add3_u32 v38, v38, v70, s73
	v_add3_u32 v34, v34, v72, s73
	v_add3_u32 v39, v39, v73, s73
	v_add3_u32 v35, v35, v74, s73
	global_store_dwordx2 v[54:55], v[32:33], off offset:32
	global_store_short_d16_hi v[58:59], v36, off
	global_store_short_d16_hi v[60:61], v40, off
	global_store_short_d16_hi v[62:63], v37, off offset:512
	global_store_short_d16_hi v[64:65], v41, off offset:512
	global_store_short_d16_hi v[66:67], v38, off offset:1024
	global_store_short_d16_hi v[48:49], v34, off offset:1024
	global_store_short_d16_hi v[50:51], v39, off offset:1536
	global_store_short_d16_hi v[68:69], v35, off offset:1536
	v_add_u32_e32 v36, 0xb0, v154
	v_ashrrev_i32_e32 v37, 31, v36
	v_lshlrev_b64 v[40:41], 7, v[36:37]
	v_lshl_add_u64 v[40:41], s[52:53], 0, v[40:41]
	v_add_u32_e32 v42, s8, v52
	v_lshl_add_u64 v[40:41], v[40:41], 0, v[136:137]
	v_ashrrev_i32_e32 v43, 31, v42
	v_add_co_u32_e32 v40, vcc, s69, v40
	v_lshl_add_u64 v[42:43], v[42:43], 1, v[152:153]
	s_nop 0
	v_addc_co_u32_e32 v41, vcc, 0, v41, vcc
	v_add_co_u32_e32 v44, vcc, s54, v42
	v_mad_i64_i32 v[38:39], s[0:1], v52, s71, v[150:151]
	s_nop 0
	v_addc_co_u32_e32 v45, vcc, 0, v43, vcc
	v_add_co_u32_e32 v46, vcc, s74, v42
	s_waitcnt vmcnt(41) lgkmcnt(0)
; DI bf16_t f2bf(float x) { unsigned u = __float_as_uint(x); u += 0x7fffu + ((u >> 16) & 1u); return (bf16_t)(u >> 16); }
; DI void st_bf16x4(bf16_t* p, f32x4 v) { u32x2 w; w.x = cvt_pk_bf16(v[0], v[1]); w.y = cvt_pk_bf16(v[2], v[3]); *(u32x2*)p = w; }
; DI float row_rstd(const unsigned char* ws, int row, int which, int fq) {
;     const f32x4 s4 = *(const f32x4*)((const float*)(ws + WS_SSQ) + (size_t)row * 32 + which * 16 + fq * 4);
;     float ss = s4[0] + s4[1] + s4[2] + s4[3];
;     ss += __shfl_xor(ss, 16); ss += __shfl_xor(ss, 32);
;     return rsqrtf(ss * (1.f / 512.f) + 1e-6f);
; }
;     DI void operator()(const f32x4 (&acc)[2][2][4][2], const Unit& u, int wr, int wc, int fr, int fq) const {
;     ...
;                 const int row = u.pm * BM + ai * HALF + wr * 64 + m * 16 + fr;
;                 const int r = row - b * RB;
;                 const float rs = row_rstd(ws, row, 1, fq);
;                 {
;                     const f32x4 v0 = acc[ai][0][m][0] * rs, v1 = acc[ai][0][m][1] * rs;
;                     bf16_t* kp = Km + (size_t)row * 640 + head * 128 + wc * 32 + 4 * fq;
;                     st_bf16x4(kp, v0); st_bf16x4(kp + 16, v1);
;                 }
;                 {
;                     const f32x4 v0 = acc[ai][1][m][0] * rs, v1 = acc[ai][1][m][1] * rs;
;                     bf16_t* vt = (bf16_t*)(ws + WS_VTM) + ((size_t)b * 640 + head * 128 + wc * 32 + 4 * fq) * RB + r;
; #pragma unroll
;                     for (int j = 0; j < 4; ++j) { vt[(size_t)j * RB] = f2bf(v0[j]); vt[(size_t)(16 + j) * RB] = f2bf(v1[j]); }
;                 }
	v_mov_b32_e32 v32, v232
	v_mov_b32_e32 v33, v233
	v_mov_b32_e32 v34, v234
	v_mov_b32_e32 v35, v235
	v_add_f32_e32 v32, v32, v33
	v_add_f32_e32 v32, v34, v32
	v_add_f32_e32 v34, v35, v32
	ds_bpermute_b32 v35, v163, v34
	v_addc_co_u32_e32 v47, vcc, 0, v43, vcc
	v_add_co_u32_e32 v48, vcc, s75, v42
	s_waitcnt lgkmcnt(0)
	v_add_f32_e32 v37, v34, v35
	v_addc_co_u32_e32 v49, vcc, 0, v43, vcc
	ds_bpermute_b32 v52, v155, v37
	v_add_co_u32_e32 v50, vcc, s42, v42
	s_waitcnt lgkmcnt(0)
	v_add_f32_e32 v37, v37, v52
	v_addc_co_u32_e32 v51, vcc, 0, v43, vcc
	v_add_co_u32_e32 v32, vcc, s55, v42
	v_fmamk_f32 v37, v37, 0x3b000000, v161
	s_nop 0
	v_addc_co_u32_e32 v33, vcc, 0, v43, vcc
	v_add_co_u32_e32 v34, vcc, s76, v42
	v_mul_f32_e32 v52, 0x4b800000, v37
	s_nop 0
	v_addc_co_u32_e32 v35, vcc, 0, v43, vcc
	v_cmp_gt_f32_e32 vcc, s70, v37
	s_nop 1
	v_cndmask_b32_e32 v37, v37, v52, vcc
	v_rsq_f32_e32 v37, v37
	v_add_co_u32_e64 v52, s[0:1], s77, v42
	v_mul_f32_e32 v54, 0x45800000, v37
	v_cndmask_b32_e32 v54, v37, v54, vcc
	v_pk_mul_f32 v[30:31], v[30:31], v[54:55] op_sel_hi:[1,0]
	v_pk_mul_f32 v[28:29], v[28:29], v[54:55] op_sel_hi:[1,0]
	v_pk_mul_f32 v[26:27], v[26:27], v[54:55] op_sel_hi:[1,0]
	v_pk_mul_f32 v[24:25], v[24:25], v[54:55] op_sel_hi:[1,0]
	v_mul_f32_e32 v20, v20, v54
	v_mul_f32_e32 v37, v16, v54
	v_mul_f32_e32 v21, v21, v54
	v_mul_f32_e32 v55, v17, v54
	v_mul_f32_e32 v22, v22, v54
	v_mul_f32_e32 v18, v18, v54
	v_mul_f32_e32 v23, v23, v54
	v_mul_f32_e32 v19, v19, v54
	v_cvt_pk_bf16_f32 v16, v28, v29
	v_cvt_pk_bf16_f32 v17, v30, v31
	v_bfe_u32 v28, v20, 16, 1
	v_bfe_u32 v29, v37, 16, 1
	v_bfe_u32 v30, v21, 16, 1
	v_bfe_u32 v31, v55, 16, 1
	v_bfe_u32 v54, v22, 16, 1
	v_bfe_u32 v56, v18, 16, 1
	v_bfe_u32 v57, v23, 16, 1
	v_bfe_u32 v58, v19, 16, 1
	global_store_dwordx2 v[38:39], v[16:17], off
	v_cvt_pk_bf16_f32 v16, v24, v25
	v_cvt_pk_bf16_f32 v17, v26, v27
	v_addc_co_u32_e64 v53, s[0:1], 0, v43, s[0:1]
	v_add3_u32 v20, v20, v28, s73
	v_add3_u32 v24, v37, v29, s73
	v_add3_u32 v21, v21, v30, s73
	v_add3_u32 v25, v55, v31, s73
	v_add3_u32 v22, v22, v54, s73
	v_add3_u32 v18, v18, v56, s73
	v_add3_u32 v23, v23, v57, s73
	v_add3_u32 v19, v19, v58, s73
	global_store_dwordx2 v[38:39], v[16:17], off offset:32
	global_store_short_d16_hi v[42:43], v20, off
	global_store_short_d16_hi v[44:45], v24, off
	global_store_short_d16_hi v[46:47], v21, off offset:512
	global_store_short_d16_hi v[48:49], v25, off offset:512
	global_store_short_d16_hi v[50:51], v22, off offset:1024
	global_store_short_d16_hi v[32:33], v18, off offset:1024
	global_store_short_d16_hi v[34:35], v23, off offset:1536
	global_store_short_d16_hi v[52:53], v19, off offset:1536
	v_add_u32_e32 v22, s8, v36
	v_ashrrev_i32_e32 v23, 31, v22
	v_lshl_add_u64 v[22:23], v[22:23], 1, v[152:153]
	v_add_co_u32_e32 v24, vcc, s54, v22
	s_and_b64 s[0:1], exec, s[6:7]
	s_nop 0
	v_addc_co_u32_e32 v25, vcc, 0, v23, vcc
	v_add_co_u32_e32 v26, vcc, s74, v22
	v_mad_i64_i32 v[20:21], s[6:7], v36, s71, v[150:151]
	s_nop 0
	v_addc_co_u32_e32 v27, vcc, 0, v23, vcc
	v_add_co_u32_e32 v28, vcc, s75, v22
	s_waitcnt vmcnt(40) lgkmcnt(0)
	v_mov_b32_e32 v16, v236
	v_mov_b32_e32 v17, v237
	v_mov_b32_e32 v18, v238
	v_mov_b32_e32 v19, v239
	v_add_f32_e32 v16, v16, v17
	v_add_f32_e32 v16, v18, v16
	v_add_f32_e32 v17, v19, v16
	ds_bpermute_b32 v18, v163, v17
	v_addc_co_u32_e32 v29, vcc, 0, v23, vcc
	v_add_co_u32_e32 v30, vcc, s42, v22
	s_waitcnt lgkmcnt(0)
	v_add_f32_e32 v19, v17, v18
	ds_bpermute_b32 v34, v155, v19
	v_addc_co_u32_e32 v31, vcc, 0, v23, vcc
	v_add_co_u32_e32 v32, vcc, s55, v22
	s_waitcnt lgkmcnt(0)
	v_add_f32_e32 v19, v19, v34
	v_fmamk_f32 v19, v19, 0x3b000000, v161
	v_mul_f32_e32 v34, 0x4b800000, v19
	v_cmp_gt_f32_e64 s[6:7], s70, v19
	v_addc_co_u32_e32 v33, vcc, 0, v23, vcc
	s_nop 0
	v_cndmask_b32_e64 v19, v19, v34, s[6:7]
	v_rsq_f32_e32 v34, v19
	v_add_co_u32_e32 v16, vcc, 0x3000, v22
	v_mul_f32_e32 v35, 0x45800000, v34
	s_nop 0
	v_addc_co_u32_e32 v17, vcc, 0, v23, vcc
	v_add_co_u32_e32 v18, vcc, 0x15000, v22
	v_cndmask_b32_e64 v34, v34, v35, s[6:7]
	s_nop 0
	v_addc_co_u32_e32 v19, vcc, 0, v23, vcc
	v_pk_mul_f32 v[14:15], v[14:15], v[34:35] op_sel_hi:[1,0]
	v_pk_mul_f32 v[12:13], v[12:13], v[34:35] op_sel_hi:[1,0]
	v_pk_mul_f32 v[10:11], v[10:11], v[34:35] op_sel_hi:[1,0]
	v_pk_mul_f32 v[8:9], v[8:9], v[34:35] op_sel_hi:[1,0]
	v_mul_f32_e32 v4, v4, v34
	v_mul_f32_e32 v35, v0, v34
	v_mul_f32_e32 v5, v5, v34
	v_mul_f32_e32 v36, v1, v34
	v_mul_f32_e32 v6, v6, v34
	v_mul_f32_e32 v2, v2, v34
	v_mul_f32_e32 v7, v7, v34
	v_mul_f32_e32 v3, v3, v34
	v_cvt_pk_bf16_f32 v0, v12, v13
	v_cvt_pk_bf16_f32 v1, v14, v15
	v_bfe_u32 v12, v4, 16, 1
	v_bfe_u32 v13, v35, 16, 1
	v_bfe_u32 v14, v5, 16, 1
	v_bfe_u32 v15, v36, 16, 1
	v_bfe_u32 v34, v6, 16, 1
	v_bfe_u32 v37, v2, 16, 1
	v_bfe_u32 v38, v7, 16, 1
	v_bfe_u32 v39, v3, 16, 1
	global_store_dwordx2 v[20:21], v[0:1], off
	v_cvt_pk_bf16_f32 v0, v8, v9
	v_cvt_pk_bf16_f32 v1, v10, v11
	s_mov_b64 vcc, s[0:1]
	v_add3_u32 v4, v4, v12, s73
	v_add3_u32 v8, v35, v13, s73
	v_add3_u32 v5, v5, v14, s73
	v_add3_u32 v9, v36, v15, s73
	v_add3_u32 v6, v6, v34, s73
	v_add3_u32 v2, v2, v37, s73
	v_add3_u32 v7, v7, v38, s73
	v_add3_u32 v3, v3, v39, s73
	global_store_dwordx2 v[20:21], v[0:1], off offset:32
	global_store_short_d16_hi v[22:23], v4, off
	global_store_short_d16_hi v[24:25], v8, off
	global_store_short_d16_hi v[26:27], v5, off offset:512
	global_store_short_d16_hi v[28:29], v9, off offset:512
	global_store_short_d16_hi v[30:31], v6, off offset:1024
	global_store_short_d16_hi v[32:33], v2, off offset:1024
	global_store_short_d16_hi v[16:17], v7, off offset:1536
	global_store_short_d16_hi v[18:19], v3, off offset:1536
	s_cbranch_vccz .LBB0_1062
	s_waitcnt vmcnt(0)
	s_cmpk_gt_u32 s2, 0xff
	s_cbranch_scc1 .LBB0_1075
	s_barrier

; #define G_STAGE(bufoff, gbase, voff) do { _Pragma("unroll") for (int _i = 0; _i < 2; ++_i) \
;         __builtin_amdgcn_global_load_lds((const unsigned*)((const char*)(gbase) + (voff)[_i]), (LAS unsigned*)(lds + (bufoff) + ldsw + _i * 8192), 16, 0, 0); } while (0)
; #define G_LDA(dst, b, h) do { _Pragma("unroll") for (int m = 0; m < 4; ++m) _Pragma("unroll") for (int k = 0; k < 2; ++k) dst[m][k] = *(const LAS bf16x8*)(lds + G_SA(b, h) + aoff + m * 2048 + k * 1024); } while (0)
; #define G_LDB(dst, b, h) do { _Pragma("unroll") for (int n = 0; n < 2; ++n) _Pragma("unroll") for (int k = 0; k < 2; ++k) dst[n][k] = *(const LAS bf16x8*)(lds + G_SB(b, h) + boff + n * 2048 + k * 1024); } while (0)
; #define G_MMA(ai, bj, At, Bt_) do { __builtin_amdgcn_s_setprio(1); _Pragma("unroll") for (int m = 0; m < 4; ++m) _Pragma("unroll") for (int n = 0; n < 2; ++n) _Pragma("unroll") for (int k = 0; k < 2; ++k) \
;         acc[ai][bj][m][n] = __builtin_amdgcn_mfma_f32_16x16x32_bf16(Bt_[n][k], At[m][k], acc[ai][bj][m][n], 0, 0, 0); __builtin_amdgcn_s_setprio(0); } while (0)
; #define G_WAIT_L(n) asm volatile("s_waitcnt lgkmcnt(" #n ")" ::: "memory")
; #define G_BAR __builtin_amdgcn_s_barrier()
; #define G_SCHED __builtin_amdgcn_sched_barrier(0)
; template <class Epi, bool PERMROWS = false>
; DI void gemm_phase(LAS unsigned char* lds, const bf16_t* A, int lda, const bf16_t* Bt, int K, const Sched& S, const Epi& E) {
;     ...
;             G_LDB(B0, 0, 0); G_SCHED; G_LDA(At, 0, 0); G_STAGE(G_SA(1, 1), a1 + hstepA, voffA);
;             G_WAIT_L(8); G_BAR; G_WAIT_L(0); G_MMA(0, 0, At, B0); G_BAR; G_SCHED;
;             G_LDB(B1, 0, 1); G_STAGE(G_SB(0, 0), b2, voffB);
;             G_BAR; G_WAIT_L(0); G_MMA(0, 1, At, B1); G_BAR;
;             G_LDA(At, 0, 1); G_STAGE(G_SA(0, 0), a2, voffA);
;             G_BAR; G_WAIT_L(0); G_MMA(1, 0, At, B0); G_BAR; G_SCHED;
.LBB0_2518:
	ds_read_b128 v[150:153], v157
	ds_read_b128 v[164:167], v157 offset:1024
	ds_read_b128 v[168:171], v157 offset:2048
	ds_read_b128 v[172:175], v157 offset:3072
	s_add_u32 s0, s18, 0x100
	s_addc_u32 s1, s19, 0
	s_cmp_eq_u32 s29, 4
	s_cselect_b32 s21, s15, s1
	s_cselect_b32 s20, s14, s0
	s_cselect_b32 s5, s13, s28
	s_cselect_b32 s4, s81, s82
	v_lshl_add_u64 v[154:155], s[18:19], 0, v[144:145]
	s_add_i32 m0, s31, 0xc000
	ds_read_b128 v[176:179], v158
	ds_read_b128 v[180:183], v158 offset:1024
	ds_read_b128 v[184:187], v158 offset:2048
	ds_read_b128 v[188:191], v158 offset:3072
	ds_read_b128 v[192:195], v158 offset:4096
	ds_read_b128 v[196:199], v158 offset:5120
	ds_read_b128 v[204:207], v158 offset:6144
	ds_read_b128 v[208:211], v158 offset:7168
	global_load_lds_dwordx4 v[154:155], off
	v_lshl_add_u64 v[154:155], s[18:19], 0, v[142:143]
	s_add_i32 m0, s31, 0xe000
	s_nop 0
	global_load_lds_dwordx4 v[154:155], off
	s_waitcnt lgkmcnt(8)
	s_barrier
	s_waitcnt lgkmcnt(0)
	s_setprio 1
	s_waitcnt lgkmcnt(0)
	v_mfma_f32_16x16x32_bf16 v[124:127], v[150:153], v[176:179], v[124:127]
	v_mfma_f32_16x16x32_bf16 v[120:123], v[168:171], v[176:179], v[120:123]
	v_mfma_f32_16x16x32_bf16 v[108:111], v[150:153], v[184:187], v[108:111]
	v_mfma_f32_16x16x32_bf16 v[104:107], v[168:171], v[184:187], v[104:107]
	v_mfma_f32_16x16x32_bf16 v[92:95], v[150:153], v[192:195], v[92:95]
	v_mfma_f32_16x16x32_bf16 v[88:91], v[168:171], v[192:195], v[88:91]
	v_mfma_f32_16x16x32_bf16 v[76:79], v[150:153], v[204:207], v[76:79]
	v_mfma_f32_16x16x32_bf16 v[72:75], v[168:171], v[204:207], v[72:75]
	v_mfma_f32_16x16x32_bf16 v[124:127], v[164:167], v[180:183], v[124:127]
	v_mfma_f32_16x16x32_bf16 v[120:123], v[172:175], v[180:183], v[120:123]
	v_mfma_f32_16x16x32_bf16 v[108:111], v[164:167], v[188:191], v[108:111]
	v_mfma_f32_16x16x32_bf16 v[104:107], v[172:175], v[188:191], v[104:107]
	v_mfma_f32_16x16x32_bf16 v[92:95], v[164:167], v[196:199], v[92:95]
	v_mfma_f32_16x16x32_bf16 v[88:91], v[172:175], v[196:199], v[88:91]
	v_mfma_f32_16x16x32_bf16 v[76:79], v[164:167], v[208:211], v[76:79]
	v_mfma_f32_16x16x32_bf16 v[72:75], v[172:175], v[208:211], v[72:75]
	s_setprio 0
	s_barrier
	s_add_i32 s18, s62, s30
	v_lshl_add_u64 v[154:155], s[4:5], 0, v[130:131]
	s_mov_b32 m0, s18
	ds_read_b128 v[212:215], v159
	ds_read_b128 v[216:219], v159 offset:1024
	ds_read_b128 v[220:223], v159 offset:2048
	ds_read_b128 v[224:227], v159 offset:3072
	global_load_lds_dwordx4 v[154:155], off
	v_lshl_add_u64 v[200:201], s[4:5], 0, v[134:135]
	s_add_i32 m0, s18, 0x2000
	s_nop 0
	global_load_lds_dwordx4 v[200:201], off
	s_barrier
	s_waitcnt lgkmcnt(0)
	s_setprio 1
	s_waitcnt lgkmcnt(0)
	v_mfma_f32_16x16x32_bf16 v[116:119], v[212:215], v[176:179], v[116:119]
	v_mfma_f32_16x16x32_bf16 v[112:115], v[220:223], v[176:179], v[112:115]
	v_mfma_f32_16x16x32_bf16 v[100:103], v[212:215], v[184:187], v[100:103]
	v_mfma_f32_16x16x32_bf16 v[96:99], v[220:223], v[184:187], v[96:99]
	v_mfma_f32_16x16x32_bf16 v[84:87], v[212:215], v[192:195], v[84:87]
	v_mfma_f32_16x16x32_bf16 v[80:83], v[220:223], v[192:195], v[80:83]
	v_mfma_f32_16x16x32_bf16 v[68:71], v[212:215], v[204:207], v[68:71]
	v_mfma_f32_16x16x32_bf16 v[64:67], v[220:223], v[204:207], v[64:67]
	v_mfma_f32_16x16x32_bf16 v[116:119], v[216:219], v[180:183], v[116:119]
	v_mfma_f32_16x16x32_bf16 v[112:115], v[224:227], v[180:183], v[112:115]
	v_mfma_f32_16x16x32_bf16 v[100:103], v[216:219], v[188:191], v[100:103]
	v_mfma_f32_16x16x32_bf16 v[96:99], v[224:227], v[188:191], v[96:99]
	v_mfma_f32_16x16x32_bf16 v[84:87], v[216:219], v[196:199], v[84:87]
	v_mfma_f32_16x16x32_bf16 v[80:83], v[224:227], v[196:199], v[80:83]
	v_mfma_f32_16x16x32_bf16 v[68:71], v[216:219], v[208:211], v[68:71]
	v_mfma_f32_16x16x32_bf16 v[64:67], v[224:227], v[208:211], v[64:67]
	s_setprio 0
	s_mov_b32 m0, s31
	v_lshl_add_u64 v[228:229], s[20:21], 0, v[128:129]
	s_barrier
	ds_read_b128 v[176:179], v158 offset:16384
	ds_read_b128 v[180:183], v158 offset:17408
	ds_read_b128 v[184:187], v158 offset:18432
	ds_read_b128 v[188:191], v158 offset:19456
	ds_read_b128 v[192:195], v158 offset:20480
	ds_read_b128 v[196:199], v158 offset:21504
	ds_read_b128 v[204:207], v158 offset:22528
	ds_read_b128 v[208:211], v158 offset:23552
	global_load_lds_dwordx4 v[228:229], off
	v_lshl_add_u64 v[230:231], s[20:21], 0, v[132:133]
	s_mov_b32 m0, s34
	s_nop 0
	global_load_lds_dwordx4 v[230:231], off
	s_barrier
	s_waitcnt lgkmcnt(0)
	s_setprio 1
	s_waitcnt lgkmcnt(0)
	v_mfma_f32_16x16x32_bf16 v[60:63], v[150:153], v[176:179], v[60:63]
	v_mfma_f32_16x16x32_bf16 v[56:59], v[168:171], v[176:179], v[56:59]
	v_mfma_f32_16x16x32_bf16 v[44:47], v[150:153], v[184:187], v[44:47]
	v_mfma_f32_16x16x32_bf16 v[40:43], v[168:171], v[184:187], v[40:43]
	v_mfma_f32_16x16x32_bf16 v[28:31], v[150:153], v[192:195], v[28:31]
	v_mfma_f32_16x16x32_bf16 v[24:27], v[168:171], v[192:195], v[24:27]
	v_mfma_f32_16x16x32_bf16 v[12:15], v[150:153], v[204:207], v[12:15]
	v_mfma_f32_16x16x32_bf16 v[8:11], v[168:171], v[204:207], v[8:11]
	v_mfma_f32_16x16x32_bf16 v[60:63], v[164:167], v[180:183], v[60:63]
	v_mfma_f32_16x16x32_bf16 v[56:59], v[172:175], v[180:183], v[56:59]
	v_mfma_f32_16x16x32_bf16 v[44:47], v[164:167], v[188:191], v[44:47]
	v_mfma_f32_16x16x32_bf16 v[40:43], v[172:175], v[188:191], v[40:43]
	v_mfma_f32_16x16x32_bf16 v[28:31], v[164:167], v[196:199], v[28:31]
	v_mfma_f32_16x16x32_bf16 v[24:27], v[172:175], v[196:199], v[24:27]
	v_mfma_f32_16x16x32_bf16 v[12:15], v[164:167], v[208:211], v[12:15]
	v_mfma_f32_16x16x32_bf16 v[8:11], v[172:175], v[208:211], v[8:11]
	s_setprio 0
	s_barrier
; #define G_STAGE(bufoff, gbase, voff) do { _Pragma("unroll") for (int _i = 0; _i < 2; ++_i) \
;         __builtin_amdgcn_global_load_lds((const unsigned*)((const char*)(gbase) + (voff)[_i]), (LAS unsigned*)(lds + (bufoff) + ldsw + _i * 8192), 16, 0, 0); } while (0)
; #define G_LDA(dst, b, h) do { _Pragma("unroll") for (int m = 0; m < 4; ++m) _Pragma("unroll") for (int k = 0; k < 2; ++k) dst[m][k] = *(const LAS bf16x8*)(lds + G_SA(b, h) + aoff + m * 2048 + k * 1024); } while (0)
; #define G_LDB(dst, b, h) do { _Pragma("unroll") for (int n = 0; n < 2; ++n) _Pragma("unroll") for (int k = 0; k < 2; ++k) dst[n][k] = *(const LAS bf16x8*)(lds + G_SB(b, h) + boff + n * 2048 + k * 1024); } while (0)
; #define G_MMA(ai, bj, At, Bt_) do { __builtin_amdgcn_s_setprio(1); _Pragma("unroll") for (int m = 0; m < 4; ++m) _Pragma("unroll") for (int n = 0; n < 2; ++n) _Pragma("unroll") for (int k = 0; k < 2; ++k) \
;         acc[ai][bj][m][n] = __builtin_amdgcn_mfma_f32_16x16x32_bf16(Bt_[n][k], At[m][k], acc[ai][bj][m][n], 0, 0, 0); __builtin_amdgcn_s_setprio(0); } while (0)
; #define G_WAIT_V(n) asm volatile("s_waitcnt vmcnt(" #n ")" ::: "memory")
; #define G_WAIT_L(n) asm volatile("s_waitcnt lgkmcnt(" #n ")" ::: "memory")
; #define G_BAR __builtin_amdgcn_s_barrier()
; #define G_SCHED __builtin_amdgcn_sched_barrier(0)
; template <class Epi, bool PERMROWS = false>
; DI void gemm_phase(LAS unsigned char* lds, const bf16_t* A, int lda, const bf16_t* Bt, int K, const Sched& S, const Epi& E) {
;     ...
;             G_STAGE(G_SB(0, 1), b2 + hstepB, voffB);
;             G_WAIT_V(6); G_BAR; G_MMA(1, 1, At, B1); G_BAR;
;             G_LDB(B0, 1, 0); G_SCHED; G_LDA(At, 1, 0); G_STAGE(G_SA(0, 1), a2 + hstepA, voffA);
;             G_WAIT_L(8); G_BAR; G_WAIT_L(0); G_MMA(0, 0, At, B0); G_BAR; G_SCHED;
;             G_LDB(B1, 1, 1); G_STAGE(G_SB(1, 0), b3, voffB);
;             G_BAR; G_WAIT_L(0); G_MMA(0, 1, At, B1); G_BAR;
;             G_LDA(At, 1, 1); G_STAGE(G_SA(1, 0), a3, voffA);
;             G_BAR; G_WAIT_L(0); G_MMA(1, 0, At, B0); G_BAR; G_SCHED;
	s_add_u32 s18, s4, 0x20000
	s_addc_u32 s19, s5, 0
	s_add_i32 s83, s63, s30
	v_lshl_add_u64 v[150:151], s[18:19], 0, v[130:131]
	s_mov_b32 m0, s83
	s_nop 0
	global_load_lds_dwordx4 v[150:151], off
	v_lshl_add_u64 v[150:151], s[18:19], 0, v[134:135]
	s_add_i32 m0, s83, 0x2000
	s_nop 0
	global_load_lds_dwordx4 v[150:151], off
	s_waitcnt vmcnt(6)
	s_barrier
	s_setprio 1
	v_mfma_f32_16x16x32_bf16 v[52:55], v[212:215], v[176:179], v[52:55]
	v_mfma_f32_16x16x32_bf16 v[48:51], v[220:223], v[176:179], v[48:51]
	v_mfma_f32_16x16x32_bf16 v[36:39], v[212:215], v[184:187], v[36:39]
	v_mfma_f32_16x16x32_bf16 v[32:35], v[220:223], v[184:187], v[32:35]
	v_mfma_f32_16x16x32_bf16 v[20:23], v[212:215], v[192:195], v[20:23]
	v_mfma_f32_16x16x32_bf16 v[16:19], v[220:223], v[192:195], v[16:19]
	v_mfma_f32_16x16x32_bf16 v[4:7], v[212:215], v[204:207], v[4:7]
	v_mfma_f32_16x16x32_bf16 v[0:3], v[220:223], v[204:207], v[0:3]
	v_mfma_f32_16x16x32_bf16 v[52:55], v[216:219], v[180:183], v[52:55]
	v_mfma_f32_16x16x32_bf16 v[48:51], v[224:227], v[180:183], v[48:51]
	v_mfma_f32_16x16x32_bf16 v[36:39], v[216:219], v[188:191], v[36:39]
	v_mfma_f32_16x16x32_bf16 v[32:35], v[224:227], v[188:191], v[32:35]
	v_mfma_f32_16x16x32_bf16 v[20:23], v[216:219], v[196:199], v[20:23]
	v_mfma_f32_16x16x32_bf16 v[16:19], v[224:227], v[196:199], v[16:19]
	v_mfma_f32_16x16x32_bf16 v[4:7], v[216:219], v[208:211], v[4:7]
	v_mfma_f32_16x16x32_bf16 v[0:3], v[224:227], v[208:211], v[0:3]
	s_setprio 0
	s_add_i32 s83, 0, 0x18000
	v_add_u32_e32 v163, s83, v156
	s_barrier
	ds_read_b128 v[150:153], v163
	ds_read_b128 v[164:167], v163 offset:1024
	ds_read_b128 v[168:171], v163 offset:2048
	ds_read_b128 v[172:175], v163 offset:3072
	s_add_u32 s18, s20, 0x180000
	s_addc_u32 s19, s21, 0
	s_mov_b32 m0, s35
	v_lshl_add_u64 v[212:213], s[18:19], 0, v[128:129]
	ds_read_b128 v[176:179], v158 offset:32768
	ds_read_b128 v[180:183], v158 offset:33792
	ds_read_b128 v[184:187], v158 offset:34816
	ds_read_b128 v[188:191], v158 offset:35840
	ds_read_b128 v[192:195], v158 offset:36864
	ds_read_b128 v[196:199], v158 offset:37888
	ds_read_b128 v[204:207], v158 offset:38912
	ds_read_b128 v[208:211], v158 offset:39936
	global_load_lds_dwordx4 v[212:213], off
	v_lshl_add_u64 v[212:213], s[18:19], 0, v[132:133]
	s_mov_b32 m0, s36
	s_nop 0
	global_load_lds_dwordx4 v[212:213], off
	s_waitcnt lgkmcnt(8)
	s_barrier
	s_waitcnt lgkmcnt(0)
	s_setprio 1
	s_waitcnt lgkmcnt(0)
	v_mfma_f32_16x16x32_bf16 v[124:127], v[150:153], v[176:179], v[124:127]
	v_mfma_f32_16x16x32_bf16 v[120:123], v[168:171], v[176:179], v[120:123]
	v_mfma_f32_16x16x32_bf16 v[108:111], v[150:153], v[184:187], v[108:111]
	v_mfma_f32_16x16x32_bf16 v[104:107], v[168:171], v[184:187], v[104:107]
	v_mfma_f32_16x16x32_bf16 v[92:95], v[150:153], v[192:195], v[92:95]
	v_mfma_f32_16x16x32_bf16 v[88:91], v[168:171], v[192:195], v[88:91]
	v_mfma_f32_16x16x32_bf16 v[76:79], v[150:153], v[204:207], v[76:79]
	v_mfma_f32_16x16x32_bf16 v[72:75], v[168:171], v[204:207], v[72:75]
	v_mfma_f32_16x16x32_bf16 v[124:127], v[164:167], v[180:183], v[124:127]
	v_mfma_f32_16x16x32_bf16 v[120:123], v[172:175], v[180:183], v[120:123]
	v_mfma_f32_16x16x32_bf16 v[108:111], v[164:167], v[188:191], v[108:111]
	v_mfma_f32_16x16x32_bf16 v[104:107], v[172:175], v[188:191], v[104:107]
	v_mfma_f32_16x16x32_bf16 v[92:95], v[164:167], v[196:199], v[92:95]
	v_mfma_f32_16x16x32_bf16 v[88:91], v[172:175], v[196:199], v[88:91]
	v_mfma_f32_16x16x32_bf16 v[76:79], v[164:167], v[208:211], v[76:79]
	v_mfma_f32_16x16x32_bf16 v[72:75], v[172:175], v[208:211], v[72:75]
	s_setprio 0
	s_barrier
	s_add_i32 s18, 0, 0x1c000
	s_add_i32 s19, s83, s30
	v_add_u32_e32 v163, s18, v156
	v_lshl_add_u64 v[154:155], v[154:155], 0, s[8:9]
	s_mov_b32 m0, s19
	ds_read_b128 v[212:215], v163
	ds_read_b128 v[216:219], v163 offset:1024
	ds_read_b128 v[220:223], v163 offset:2048
	ds_read_b128 v[224:227], v163 offset:3072
	global_load_lds_dwordx4 v[154:155], off
	v_lshl_add_u64 v[154:155], v[200:201], 0, s[8:9]
	s_add_i32 m0, s19, 0x2000
	s_nop 0
	global_load_lds_dwordx4 v[154:155], off
	s_barrier
	s_waitcnt lgkmcnt(0)
	s_setprio 1
	s_waitcnt lgkmcnt(0)
	v_mfma_f32_16x16x32_bf16 v[116:119], v[212:215], v[176:179], v[116:119]
	v_mfma_f32_16x16x32_bf16 v[112:115], v[220:223], v[176:179], v[112:115]
	v_mfma_f32_16x16x32_bf16 v[100:103], v[212:215], v[184:187], v[100:103]
	v_mfma_f32_16x16x32_bf16 v[96:99], v[220:223], v[184:187], v[96:99]
	v_mfma_f32_16x16x32_bf16 v[84:87], v[212:215], v[192:195], v[84:87]
	v_mfma_f32_16x16x32_bf16 v[80:83], v[220:223], v[192:195], v[80:83]
	v_mfma_f32_16x16x32_bf16 v[68:71], v[212:215], v[204:207], v[68:71]
	v_mfma_f32_16x16x32_bf16 v[64:67], v[220:223], v[204:207], v[64:67]
	v_mfma_f32_16x16x32_bf16 v[116:119], v[216:219], v[180:183], v[116:119]
	v_mfma_f32_16x16x32_bf16 v[112:115], v[224:227], v[180:183], v[112:115]
	v_mfma_f32_16x16x32_bf16 v[100:103], v[216:219], v[188:191], v[100:103]
	v_mfma_f32_16x16x32_bf16 v[96:99], v[224:227], v[188:191], v[96:99]
	v_mfma_f32_16x16x32_bf16 v[84:87], v[216:219], v[196:199], v[84:87]
	v_mfma_f32_16x16x32_bf16 v[80:83], v[224:227], v[196:199], v[80:83]
	v_mfma_f32_16x16x32_bf16 v[68:71], v[216:219], v[208:211], v[68:71]
	v_mfma_f32_16x16x32_bf16 v[64:67], v[224:227], v[208:211], v[64:67]
	s_setprio 0
	s_mov_b32 m0, s56
	v_lshl_add_u64 v[154:155], v[228:229], 0, s[8:9]
	s_barrier
	ds_read_b128 v[176:179], v158 offset:49152
	ds_read_b128 v[180:183], v158 offset:50176
	ds_read_b128 v[184:187], v158 offset:51200
	ds_read_b128 v[188:191], v158 offset:52224
	ds_read_b128 v[192:195], v158 offset:53248
	ds_read_b128 v[196:199], v158 offset:54272
	ds_read_b128 v[204:207], v158 offset:55296
	ds_read_b128 v[208:211], v158 offset:56320
	global_load_lds_dwordx4 v[154:155], off
	v_lshl_add_u64 v[154:155], v[230:231], 0, s[8:9]
	s_mov_b32 m0, s57
	s_nop 0
	global_load_lds_dwordx4 v[154:155], off
	s_barrier
; #define G_STAGE(bufoff, gbase, voff) do { _Pragma("unroll") for (int _i = 0; _i < 2; ++_i) \
;         __builtin_amdgcn_global_load_lds((const unsigned*)((const char*)(gbase) + (voff)[_i]), (LAS unsigned*)(lds + (bufoff) + ldsw + _i * 8192), 16, 0, 0); } while (0)
; #define G_MMA(ai, bj, At, Bt_) do { __builtin_amdgcn_s_setprio(1); _Pragma("unroll") for (int m = 0; m < 4; ++m) _Pragma("unroll") for (int n = 0; n < 2; ++n) _Pragma("unroll") for (int k = 0; k < 2; ++k) \
;         acc[ai][bj][m][n] = __builtin_amdgcn_mfma_f32_16x16x32_bf16(Bt_[n][k], At[m][k], acc[ai][bj][m][n], 0, 0, 0); __builtin_amdgcn_s_setprio(0); } while (0)
; #define G_WAIT_V(n) asm volatile("s_waitcnt vmcnt(" #n ")" ::: "memory")
; #define G_WAIT_L(n) asm volatile("s_waitcnt lgkmcnt(" #n ")" ::: "memory")
; #define G_BAR __builtin_amdgcn_s_barrier()
; #define G_SCHED __builtin_amdgcn_sched_barrier(0)
; DI void st_bf16x4(bf16_t* p, f32x4 v) { u32x2 w; w.x = cvt_pk_bf16(v[0], v[1]); w.y = cvt_pk_bf16(v[2], v[3]); *(u32x2*)p = w; }
; template <class Epi, bool PERMROWS = false>
; DI void gemm_phase(LAS unsigned char* lds, const bf16_t* A, int lda, const bf16_t* Bt, int K, const Sched& S, const Epi& E) {
;     ...
;             G_BAR; G_WAIT_L(0); G_MMA(1, 0, At, B0); G_BAR; G_SCHED;
;             G_STAGE(G_SB(1, 1), b3 + hstepB, voffB);
;             G_WAIT_V(6); G_BAR; G_MMA(1, 1, At, B1); G_BAR;
;         }
;         E(acc, cur, wr, wc, fr, fq);
;         if (!has_next) break;
;     DI void operator()(const f32x4 (&acc)[2][2][4][2], const Unit& u, int wr, int wc, int fr, int fq) const {
;         bf16_t* Km = (bf16_t*)(ws + WS_KM);
;         const int b = u.pm / 9, head = u.pn;
; #pragma unroll
;         for (int ai = 0; ai < 2; ++ai)
; #pragma unroll
;             for (int m = 0; m < 4; ++m) {
;                 const int row = u.pm * BM + ai * HALF + wr * 64 + m * 16 + fr;
;                 const int r = row - b * RB;
;                 const float rs = row_rstd(ws, row, 1, fq);
;                 {
;                     const f32x4 v0 = acc[ai][0][m][0] * rs, v1 = acc[ai][0][m][1] * rs;
;                     bf16_t* kp = Km + (size_t)row * 640 + head * 128 + wc * 32 + 4 * fq;
;                     st_bf16x4(kp, v0); st_bf16x4(kp + 16, v1);
	s_waitcnt lgkmcnt(0)
	s_setprio 1
	s_waitcnt lgkmcnt(0)
	v_mfma_f32_16x16x32_bf16 v[60:63], v[150:153], v[176:179], v[60:63]
	v_mfma_f32_16x16x32_bf16 v[56:59], v[168:171], v[176:179], v[56:59]
	v_mfma_f32_16x16x32_bf16 v[44:47], v[150:153], v[184:187], v[44:47]
	v_mfma_f32_16x16x32_bf16 v[40:43], v[168:171], v[184:187], v[40:43]
	v_mfma_f32_16x16x32_bf16 v[28:31], v[150:153], v[192:195], v[28:31]
	v_mfma_f32_16x16x32_bf16 v[24:27], v[168:171], v[192:195], v[24:27]
	v_mfma_f32_16x16x32_bf16 v[12:15], v[150:153], v[204:207], v[12:15]
	v_mfma_f32_16x16x32_bf16 v[8:11], v[168:171], v[204:207], v[8:11]
	v_mfma_f32_16x16x32_bf16 v[60:63], v[164:167], v[180:183], v[60:63]
	v_mfma_f32_16x16x32_bf16 v[56:59], v[172:175], v[180:183], v[56:59]
	v_mfma_f32_16x16x32_bf16 v[44:47], v[164:167], v[188:191], v[44:47]
	v_mfma_f32_16x16x32_bf16 v[40:43], v[172:175], v[188:191], v[40:43]
	v_mfma_f32_16x16x32_bf16 v[28:31], v[164:167], v[196:199], v[28:31]
	v_mfma_f32_16x16x32_bf16 v[24:27], v[172:175], v[196:199], v[24:27]
	v_mfma_f32_16x16x32_bf16 v[12:15], v[164:167], v[208:211], v[12:15]
	v_mfma_f32_16x16x32_bf16 v[8:11], v[172:175], v[208:211], v[8:11]
	s_setprio 0
	s_barrier
	s_add_u32 s4, s4, 0x20080
	s_addc_u32 s5, s5, 0
	s_add_i32 s18, s18, s30
	v_lshl_add_u64 v[150:151], s[4:5], 0, v[130:131]
	s_mov_b32 m0, s18
	s_nop 0
	global_load_lds_dwordx4 v[150:151], off
	v_lshl_add_u64 v[150:151], s[4:5], 0, v[134:135]
	s_add_i32 m0, s18, 0x2000
	s_nop 0
	global_load_lds_dwordx4 v[150:151], off
	s_waitcnt vmcnt(6)
	s_barrier
	s_setprio 1
	v_mfma_f32_16x16x32_bf16 v[52:55], v[212:215], v[176:179], v[52:55]
	v_mfma_f32_16x16x32_bf16 v[48:51], v[220:223], v[176:179], v[48:51]
	v_mfma_f32_16x16x32_bf16 v[36:39], v[212:215], v[184:187], v[36:39]
	v_mfma_f32_16x16x32_bf16 v[32:35], v[220:223], v[184:187], v[32:35]
	v_mfma_f32_16x16x32_bf16 v[20:23], v[212:215], v[192:195], v[20:23]
	v_mfma_f32_16x16x32_bf16 v[16:19], v[220:223], v[192:195], v[16:19]
	v_mfma_f32_16x16x32_bf16 v[4:7], v[212:215], v[204:207], v[4:7]
	v_mfma_f32_16x16x32_bf16 v[0:3], v[220:223], v[204:207], v[0:3]
	v_mfma_f32_16x16x32_bf16 v[52:55], v[216:219], v[180:183], v[52:55]
	v_mfma_f32_16x16x32_bf16 v[48:51], v[224:227], v[180:183], v[48:51]
	v_mfma_f32_16x16x32_bf16 v[36:39], v[216:219], v[188:191], v[36:39]
	v_mfma_f32_16x16x32_bf16 v[32:35], v[224:227], v[188:191], v[32:35]
	v_mfma_f32_16x16x32_bf16 v[20:23], v[216:219], v[196:199], v[20:23]
	v_mfma_f32_16x16x32_bf16 v[16:19], v[224:227], v[196:199], v[16:19]
	v_mfma_f32_16x16x32_bf16 v[4:7], v[216:219], v[208:211], v[4:7]
	v_mfma_f32_16x16x32_bf16 v[0:3], v[224:227], v[208:211], v[0:3]
	s_setprio 0
	s_add_i32 s29, s29, 2
	s_add_u32 s82, s82, 0x100
	s_addc_u32 s28, s28, 0
	s_cmp_gt_u32 s29, 5
	s_mov_b64 s[18:19], s[0:1]
	s_barrier
	s_cbranch_scc0 .LBB0_2518
	v_lshl_add_u32 v154, s78, 8, v141
	v_ashrrev_i32_e32 v155, 31, v154
	v_lshlrev_b64 v[150:151], 7, v[154:155]
	v_lshl_add_u64 v[150:151], s[52:53], 0, v[150:151]
	v_lshl_add_u64 v[150:151], v[150:151], 0, v[136:137]
	v_add_co_u32_e32 v150, vcc, s68, v150
	s_mul_hi_i32 s1, s78, 0x38e38e39
	s_nop 0
	v_addc_co_u32_e32 v151, vcc, 0, v151, vcc
	global_load_dwordx4 v[164:167], v[150:151], off offset:64
	s_mov_b64 s[98:99], 0x800
	v_lshl_add_u64 v[232:233], s[98:99], 0, v[150:151]
	global_load_dwordx4 v[232:235], v[232:233], off offset:64
	s_mov_b64 s[98:99], 0x1000
	v_lshl_add_u64 v[236:237], s[98:99], 0, v[150:151]
	global_load_dwordx4 v[236:239], v[236:237], off offset:64
	s_mov_b64 s[98:99], 0x1800
	v_lshl_add_u64 v[240:241], s[98:99], 0, v[150:151]
	global_load_dwordx4 v[240:243], v[240:241], off offset:64
	s_mov_b64 s[98:99], 0x4000
	v_lshl_add_u64 v[244:245], s[98:99], 0, v[150:151]
	global_load_dwordx4 v[244:247], v[244:245], off offset:64
	s_mov_b64 s[98:99], 0x4800
	v_lshl_add_u64 v[248:249], s[98:99], 0, v[150:151]
	global_load_dwordx4 v[248:251], v[248:249], off offset:64
	v_and_b32_e32 v151, 64, v160
	v_xor_b32_e32 v150, 16, v160
	v_add_u32_e32 v151, 64, v151
	v_cmp_lt_i32_e32 vcc, v150, v151
	s_lshl_b32 s0, s79, 7
	s_lshr_b32 s4, s1, 31
	v_cndmask_b32_e32 v163, v160, v150, vcc
	s_ashr_i32 s5, s1, 1
	s_ashr_i32 s1, s0, 31
	v_lshlrev_b32_e32 v163, 2, v163
	v_xor_b32_e32 v155, 32, v160
	v_or_b32_e32 v168, s0, v140
	s_add_i32 s5, s5, s4
	v_mov_b32_e32 v169, s1
	v_mov_b64_e32 v[152:153], s[10:11]
	v_cmp_lt_i32_e32 vcc, v155, v151
	v_lshl_add_u64 v[150:151], s[0:1], 1, v[138:139]
	s_mul_i32 s4, s5, 0xfffff700
	v_mad_i64_i32 v[168:169], s[0:1], s5, v162, v[168:169]
	v_add_u32_e32 v172, s4, v154
	v_mad_u64_u32 v[152:153], s[0:1], v168, s71, v[152:153]
	v_mad_i32_i24 v153, v169, s71, v153
	v_ashrrev_i32_e32 v173, 31, v172
	v_cndmask_b32_e32 v155, v160, v155, vcc
	v_lshl_add_u64 v[168:169], v[172:173], 1, v[152:153]
	v_lshlrev_b32_e32 v155, 2, v155
	v_add_co_u32_e32 v172, vcc, s43, v168
	v_mad_i64_i32 v[170:171], s[0:1], v154, s70, v[150:151]
	s_nop 0
	v_addc_co_u32_e32 v173, vcc, 0, v169, vcc
	v_add_co_u32_e32 v174, vcc, s73, v168
	s_mov_b32 s79, s12
	s_nop 0
	v_addc_co_u32_e32 v175, vcc, 0, v169, vcc
	s_mov_b32 s78, s77
	s_mov_b64 s[20:21], s[16:17]
	s_mov_b64 s[18:19], s[14:15]
	s_waitcnt vmcnt(5) lgkmcnt(0)
	v_add_f32_e32 v164, v164, v165
	v_add_f32_e32 v164, v166, v164
	v_add_f32_e32 v166, v167, v164
	ds_bpermute_b32 v167, v163, v166
	v_add_co_u32_e32 v164, vcc, s74, v168
	s_waitcnt lgkmcnt(0)
	v_add_f32_e32 v176, v166, v167
	ds_bpermute_b32 v177, v155, v176
	v_addc_co_u32_e32 v165, vcc, 0, v169, vcc
	v_add_co_u32_e32 v166, vcc, s37, v168
	s_waitcnt lgkmcnt(0)
; DI bf16_t f2bf(float x) { unsigned u = __float_as_uint(x); u += 0x7fffu + ((u >> 16) & 1u); return (bf16_t)(u >> 16); }
; DI void st_bf16x4(bf16_t* p, f32x4 v) { u32x2 w; w.x = cvt_pk_bf16(v[0], v[1]); w.y = cvt_pk_bf16(v[2], v[3]); *(u32x2*)p = w; }
; DI float row_rstd(const unsigned char* ws, int row, int which, int fq) {
;     const f32x4 s4 = *(const f32x4*)((const float*)(ws + WS_SSQ) + (size_t)row * 32 + which * 16 + fq * 4);
;     float ss = s4[0] + s4[1] + s4[2] + s4[3];
;     ss += __shfl_xor(ss, 16); ss += __shfl_xor(ss, 32);
;     return rsqrtf(ss * (1.f / 512.f) + 1e-6f);
; }
;     DI void operator()(const f32x4 (&acc)[2][2][4][2], const Unit& u, int wr, int wc, int fr, int fq) const {
;     ...
;         for (int ai = 0; ai < 2; ++ai)
; #pragma unroll
;             for (int m = 0; m < 4; ++m) {
;                 const int row = u.pm * BM + ai * HALF + wr * 64 + m * 16 + fr;
;                 const int r = row - b * RB;
;                 const float rs = row_rstd(ws, row, 1, fq);
;                 {
;                     const f32x4 v0 = acc[ai][0][m][0] * rs, v1 = acc[ai][0][m][1] * rs;
;                     bf16_t* kp = Km + (size_t)row * 640 + head * 128 + wc * 32 + 4 * fq;
;                     st_bf16x4(kp, v0); st_bf16x4(kp + 16, v1);
;                 }
;                 {
;                     const f32x4 v0 = acc[ai][1][m][0] * rs, v1 = acc[ai][1][m][1] * rs;
;                     bf16_t* vt = (bf16_t*)(ws + WS_VTM) + ((size_t)b * 640 + head * 128 + wc * 32 + 4 * fq) * RB + r;
; #pragma unroll
;                     for (int j = 0; j < 4; ++j) { vt[(size_t)j * RB] = f2bf(v0[j]); vt[(size_t)(16 + j) * RB] = f2bf(v1[j]); }
;                 }
	v_add_f32_e32 v176, v176, v177
	v_addc_co_u32_e32 v167, vcc, 0, v169, vcc
	v_fmamk_f32 v176, v176, 0x3b000000, v161
	v_mul_f32_e32 v177, 0x4b800000, v176
	v_cmp_gt_f32_e32 vcc, s69, v176
	s_nop 1
	v_cndmask_b32_e32 v176, v176, v177, vcc
	v_rsq_f32_e32 v178, v176
	v_add_co_u32_e64 v176, s[0:1], s54, v168
	v_mul_f32_e32 v179, 0x45800000, v178
	v_cndmask_b32_e32 v178, v178, v179, vcc
	v_pk_mul_f32 v[126:127], v[126:127], v[178:179] op_sel_hi:[1,0]
	v_pk_mul_f32 v[124:125], v[124:125], v[178:179] op_sel_hi:[1,0]
	v_pk_mul_f32 v[122:123], v[122:123], v[178:179] op_sel_hi:[1,0]
	v_pk_mul_f32 v[120:121], v[120:121], v[178:179] op_sel_hi:[1,0]
	v_mul_f32_e32 v116, v116, v178
	v_mul_f32_e32 v179, v112, v178
	v_mul_f32_e32 v117, v117, v178
	v_mul_f32_e32 v180, v113, v178
	v_mul_f32_e32 v118, v118, v178
	v_mul_f32_e32 v114, v114, v178
	v_cvt_pk_bf16_f32 v112, v124, v125
	v_cvt_pk_bf16_f32 v113, v126, v127
	v_mul_f32_e32 v119, v119, v178
	v_bfe_u32 v124, v116, 16, 1
	v_bfe_u32 v125, v179, 16, 1
	v_bfe_u32 v126, v117, 16, 1
	v_bfe_u32 v127, v180, 16, 1
	v_bfe_u32 v181, v118, 16, 1
	v_bfe_u32 v182, v114, 16, 1
	global_store_dwordx2 v[170:171], v[112:113], off
	v_cvt_pk_bf16_f32 v112, v120, v121
	v_cvt_pk_bf16_f32 v113, v122, v123
	v_addc_co_u32_e64 v177, s[0:1], 0, v169, s[0:1]
	v_bfe_u32 v183, v119, 16, 1
	v_add3_u32 v116, v116, v124, s72
	v_add3_u32 v120, v179, v125, s72
	v_add3_u32 v117, v117, v126, s72
	v_add3_u32 v121, v180, v127, s72
	v_add3_u32 v118, v118, v181, s72
	v_add3_u32 v114, v114, v182, s72
	global_store_dwordx2 v[170:171], v[112:113], off offset:32
	global_store_short_d16_hi v[168:169], v116, off
	global_store_short_d16_hi v[172:173], v120, off
	global_store_short_d16_hi v[174:175], v117, off offset:512
	global_store_short_d16_hi v[164:165], v121, off offset:512
	global_store_short_d16_hi v[166:167], v118, off offset:1024
	global_store_short_d16_hi v[176:177], v114, off offset:1024
	v_add_co_u32_e32 v112, vcc, s75, v168
	v_add3_u32 v119, v119, v183, s72
	s_nop 0
	v_addc_co_u32_e32 v113, vcc, 0, v169, vcc
	global_store_short_d16_hi v[112:113], v119, off offset:1536
	v_mul_f32_e32 v112, v115, v178
	v_bfe_u32 v113, v112, 16, 1
	v_add3_u32 v114, v112, v113, s72
	v_add_co_u32_e32 v112, vcc, s76, v168
	v_or_b32_e32 v116, 16, v154
	s_nop 0
	v_addc_co_u32_e32 v113, vcc, 0, v169, vcc
	v_ashrrev_i32_e32 v117, 31, v116
	global_store_short_d16_hi v[112:113], v114, off offset:1536
	v_lshlrev_b64 v[112:113], 7, v[116:117]
	v_lshl_add_u64 v[112:113], s[52:53], 0, v[112:113]
	v_lshl_add_u64 v[112:113], v[112:113], 0, v[136:137]
	v_add_co_u32_e32 v112, vcc, s68, v112
	v_mad_i64_i32 v[118:119], s[0:1], v116, s70, v[150:151]
	s_nop 0
	v_addc_co_u32_e32 v113, vcc, 0, v113, vcc
	v_add_u32_e32 v116, s4, v116
	v_ashrrev_i32_e32 v117, 31, v116
	v_lshl_add_u64 v[116:117], v[116:117], 1, v[152:153]
	v_add_co_u32_e32 v120, vcc, s43, v116
	s_waitcnt vmcnt(14) lgkmcnt(0)
	v_mov_b32_e32 v112, v232
	v_mov_b32_e32 v113, v233
	v_mov_b32_e32 v114, v234
	v_mov_b32_e32 v115, v235
	v_add_f32_e32 v112, v112, v113
	v_add_f32_e32 v112, v114, v112
	v_add_f32_e32 v114, v115, v112
	ds_bpermute_b32 v115, v163, v114
	v_addc_co_u32_e32 v121, vcc, 0, v117, vcc
	v_add_co_u32_e32 v122, vcc, s73, v116
	s_waitcnt lgkmcnt(0)
	v_add_f32_e32 v126, v114, v115
	v_addc_co_u32_e32 v123, vcc, 0, v117, vcc
	ds_bpermute_b32 v127, v155, v126
	v_add_co_u32_e32 v124, vcc, s74, v116
	s_waitcnt lgkmcnt(0)
	v_add_f32_e32 v126, v126, v127
	v_addc_co_u32_e32 v125, vcc, 0, v117, vcc
	v_add_co_u32_e32 v112, vcc, s37, v116
	v_fmamk_f32 v126, v126, 0x3b000000, v161
	s_nop 0
	v_addc_co_u32_e32 v113, vcc, 0, v117, vcc
	v_add_co_u32_e32 v114, vcc, s54, v116
	v_mul_f32_e32 v127, 0x4b800000, v126
	s_nop 0
	v_addc_co_u32_e32 v115, vcc, 0, v117, vcc
	v_cmp_gt_f32_e32 vcc, s69, v126
	s_nop 1
	v_cndmask_b32_e32 v126, v126, v127, vcc
	v_rsq_f32_e32 v164, v126
	v_add_co_u32_e64 v126, s[0:1], s75, v116
	v_mul_f32_e32 v165, 0x45800000, v164
	v_cndmask_b32_e32 v164, v164, v165, vcc
	v_pk_mul_f32 v[108:109], v[108:109], v[164:165] op_sel_hi:[1,0]
	v_mul_f32_e32 v100, v100, v164
	v_pk_mul_f32 v[110:111], v[110:111], v[164:165] op_sel_hi:[1,0]
	v_pk_mul_f32 v[106:107], v[106:107], v[164:165] op_sel_hi:[1,0]
	v_pk_mul_f32 v[104:105], v[104:105], v[164:165] op_sel_hi:[1,0]
	v_mul_f32_e32 v165, v96, v164
	v_mul_f32_e32 v101, v101, v164
	v_mul_f32_e32 v166, v97, v164
	v_mul_f32_e32 v102, v102, v164
	v_mul_f32_e32 v98, v98, v164
	v_mul_f32_e32 v103, v103, v164
	v_cvt_pk_bf16_f32 v96, v108, v109
	v_cvt_pk_bf16_f32 v97, v110, v111
	v_bfe_u32 v108, v100, 16, 1
	v_mul_f32_e32 v99, v99, v164
	v_bfe_u32 v109, v165, 16, 1
	v_bfe_u32 v110, v101, 16, 1
	v_bfe_u32 v111, v166, 16, 1
	v_bfe_u32 v164, v102, 16, 1
	v_bfe_u32 v167, v98, 16, 1
	v_bfe_u32 v168, v103, 16, 1
	global_store_dwordx2 v[118:119], v[96:97], off
	v_cvt_pk_bf16_f32 v96, v104, v105
	v_cvt_pk_bf16_f32 v97, v106, v107
	v_add3_u32 v100, v100, v108, s72
	v_addc_co_u32_e64 v127, s[0:1], 0, v117, s[0:1]
	v_bfe_u32 v169, v99, 16, 1
	v_add3_u32 v104, v165, v109, s72
	v_add3_u32 v101, v101, v110, s72
	v_add3_u32 v105, v166, v111, s72
	v_add3_u32 v102, v102, v164, s72
	v_add3_u32 v98, v98, v167, s72
	v_add3_u32 v103, v103, v168, s72
	global_store_dwordx2 v[118:119], v[96:97], off offset:32
	global_store_short_d16_hi v[116:117], v100, off
	global_store_short_d16_hi v[120:121], v104, off
	global_store_short_d16_hi v[122:123], v101, off offset:512
	global_store_short_d16_hi v[124:125], v105, off offset:512
	global_store_short_d16_hi v[112:113], v102, off offset:1024
	global_store_short_d16_hi v[114:115], v98, off offset:1024
	global_store_short_d16_hi v[126:127], v103, off offset:1536
	v_add_co_u32_e32 v96, vcc, s76, v116
	v_or_b32_e32 v100, 32, v154
	v_add3_u32 v99, v99, v169, s72
	v_addc_co_u32_e32 v97, vcc, 0, v117, vcc
	v_ashrrev_i32_e32 v101, 31, v100
	global_store_short_d16_hi v[96:97], v99, off offset:1536
	v_lshlrev_b64 v[96:97], 7, v[100:101]
	v_lshl_add_u64 v[96:97], s[52:53], 0, v[96:97]
	v_lshl_add_u64 v[96:97], v[96:97], 0, v[136:137]
	v_add_co_u32_e32 v96, vcc, s68, v96
	v_mad_i64_i32 v[104:105], s[0:1], v100, s70, v[150:151]
	s_nop 0
	v_addc_co_u32_e32 v97, vcc, 0, v97, vcc
	s_mov_b64 s[98:99], 0x4000
	v_lshl_add_u64 v[232:233], s[98:99], 0, v[96:97]
	global_load_dwordx4 v[232:235], v[232:233], off offset:64
	v_add_u32_e32 v100, s4, v100
	v_ashrrev_i32_e32 v101, 31, v100
	v_lshl_add_u64 v[100:101], v[100:101], 1, v[152:153]
	v_add_co_u32_e32 v108, vcc, s43, v100
	v_or_b32_e32 v102, 48, v154
	s_nop 0
	v_addc_co_u32_e32 v109, vcc, 0, v101, vcc
	v_add_co_u32_e32 v110, vcc, s73, v100
	v_ashrrev_i32_e32 v103, 31, v102
	s_nop 0
	v_addc_co_u32_e32 v111, vcc, 0, v101, vcc
	v_lshlrev_b64 v[106:107], 7, v[102:103]
	v_add_co_u32_e32 v112, vcc, s74, v100
	v_lshl_add_u64 v[106:107], s[52:53], 0, v[106:107]
	s_nop 0
	v_addc_co_u32_e32 v113, vcc, 0, v101, vcc
	v_add_co_u32_e32 v114, vcc, s37, v100
	v_lshl_add_u64 v[106:107], v[106:107], 0, v[136:137]
	s_nop 0
	v_addc_co_u32_e32 v115, vcc, 0, v101, vcc
	s_waitcnt vmcnt(24) lgkmcnt(0)
; DI bf16_t f2bf(float x) { unsigned u = __float_as_uint(x); u += 0x7fffu + ((u >> 16) & 1u); return (bf16_t)(u >> 16); }
; DI void st_bf16x4(bf16_t* p, f32x4 v) { u32x2 w; w.x = cvt_pk_bf16(v[0], v[1]); w.y = cvt_pk_bf16(v[2], v[3]); *(u32x2*)p = w; }
; DI float row_rstd(const unsigned char* ws, int row, int which, int fq) {
;     const f32x4 s4 = *(const f32x4*)((const float*)(ws + WS_SSQ) + (size_t)row * 32 + which * 16 + fq * 4);
;     float ss = s4[0] + s4[1] + s4[2] + s4[3];
;     ss += __shfl_xor(ss, 16); ss += __shfl_xor(ss, 32);
;     return rsqrtf(ss * (1.f / 512.f) + 1e-6f);
; }
;     DI void operator()(const f32x4 (&acc)[2][2][4][2], const Unit& u, int wr, int wc, int fr, int fq) const {
;     ...
;         for (int ai = 0; ai < 2; ++ai)
; #pragma unroll
;             for (int m = 0; m < 4; ++m) {
;                 const int row = u.pm * BM + ai * HALF + wr * 64 + m * 16 + fr;
;                 const int r = row - b * RB;
;                 const float rs = row_rstd(ws, row, 1, fq);
;                 {
;                     const f32x4 v0 = acc[ai][0][m][0] * rs, v1 = acc[ai][0][m][1] * rs;
;                     bf16_t* kp = Km + (size_t)row * 640 + head * 128 + wc * 32 + 4 * fq;
;                     st_bf16x4(kp, v0); st_bf16x4(kp + 16, v1);
;                 }
;                 {
;                     const f32x4 v0 = acc[ai][1][m][0] * rs, v1 = acc[ai][1][m][1] * rs;
;                     bf16_t* vt = (bf16_t*)(ws + WS_VTM) + ((size_t)b * 640 + head * 128 + wc * 32 + 4 * fq) * RB + r;
; #pragma unroll
;                     for (int j = 0; j < 4; ++j) { vt[(size_t)j * RB] = f2bf(v0[j]); vt[(size_t)(16 + j) * RB] = f2bf(v1[j]); }
;                 }
	v_mov_b32_e32 v96, v236
	v_mov_b32_e32 v97, v237
	v_mov_b32_e32 v98, v238
	v_mov_b32_e32 v99, v239
	v_add_f32_e32 v96, v96, v97
	v_add_f32_e32 v96, v98, v96
	v_add_f32_e32 v98, v99, v96
	ds_bpermute_b32 v99, v163, v98
	v_add_co_u32_e32 v96, vcc, s54, v100
	s_waitcnt lgkmcnt(0)
	v_add_f32_e32 v103, v98, v99
	ds_bpermute_b32 v116, v155, v103
	v_addc_co_u32_e32 v97, vcc, 0, v101, vcc
	v_add_co_u32_e32 v98, vcc, s75, v100
	s_waitcnt lgkmcnt(0)
	v_add_f32_e32 v103, v103, v116
	v_addc_co_u32_e32 v99, vcc, 0, v101, vcc
	v_fmamk_f32 v103, v103, 0x3b000000, v161
	v_mul_f32_e32 v116, 0x4b800000, v103
	v_cmp_gt_f32_e32 vcc, s69, v103
	s_nop 1
	v_cndmask_b32_e32 v103, v103, v116, vcc
	v_rsq_f32_e32 v103, v103
	v_add_co_u32_e64 v116, s[0:1], s76, v100
	v_mul_f32_e32 v118, 0x45800000, v103
	v_cndmask_b32_e32 v118, v103, v118, vcc
	v_pk_mul_f32 v[94:95], v[94:95], v[118:119] op_sel_hi:[1,0]
	v_pk_mul_f32 v[92:93], v[92:93], v[118:119] op_sel_hi:[1,0]
	v_pk_mul_f32 v[90:91], v[90:91], v[118:119] op_sel_hi:[1,0]
	v_pk_mul_f32 v[88:89], v[88:89], v[118:119] op_sel_hi:[1,0]
	v_mul_f32_e32 v84, v84, v118
	v_mul_f32_e32 v103, v80, v118
	v_mul_f32_e32 v85, v85, v118
	v_mul_f32_e32 v119, v81, v118
	v_mul_f32_e32 v86, v86, v118
	v_mul_f32_e32 v82, v82, v118
	v_mul_f32_e32 v87, v87, v118
	v_mul_f32_e32 v83, v83, v118
	v_cvt_pk_bf16_f32 v80, v92, v93
	v_cvt_pk_bf16_f32 v81, v94, v95
	v_bfe_u32 v92, v84, 16, 1
	v_bfe_u32 v93, v103, 16, 1
	v_bfe_u32 v94, v85, 16, 1
	v_bfe_u32 v95, v119, 16, 1
	v_bfe_u32 v118, v86, 16, 1
	v_bfe_u32 v120, v82, 16, 1
	v_bfe_u32 v121, v87, 16, 1
	v_bfe_u32 v122, v83, 16, 1
	global_store_dwordx2 v[104:105], v[80:81], off
	v_cvt_pk_bf16_f32 v80, v88, v89
	v_cvt_pk_bf16_f32 v81, v90, v91
	v_addc_co_u32_e64 v117, s[0:1], 0, v101, s[0:1]
	v_add3_u32 v84, v84, v92, s72
	v_add3_u32 v88, v103, v93, s72
	v_add3_u32 v85, v85, v94, s72
	v_add3_u32 v89, v119, v95, s72
	v_add3_u32 v86, v86, v118, s72
	v_add3_u32 v82, v82, v120, s72
	v_add3_u32 v87, v87, v121, s72
	v_add3_u32 v83, v83, v122, s72
	global_store_dwordx2 v[104:105], v[80:81], off offset:32
	global_store_short_d16_hi v[100:101], v84, off
	global_store_short_d16_hi v[108:109], v88, off
	global_store_short_d16_hi v[110:111], v85, off offset:512
	global_store_short_d16_hi v[112:113], v89, off offset:512
	global_store_short_d16_hi v[114:115], v86, off offset:1024
	global_store_short_d16_hi v[96:97], v82, off offset:1024
	global_store_short_d16_hi v[98:99], v87, off offset:1536
	global_store_short_d16_hi v[116:117], v83, off offset:1536
	v_add_co_u32_e32 v80, vcc, s68, v106
	v_add_u32_e32 v84, 0x80, v154
	s_nop 0
	v_addc_co_u32_e32 v81, vcc, 0, v107, vcc
	s_mov_b64 s[98:99], 0x4000
	v_lshl_add_u64 v[236:237], s[98:99], 0, v[80:81]
	global_load_dwordx4 v[236:239], v[236:237], off offset:64
	v_ashrrev_i32_e32 v85, 31, v84
	v_lshlrev_b64 v[88:89], 7, v[84:85]
	v_lshl_add_u64 v[88:89], s[52:53], 0, v[88:89]
	v_add_u32_e32 v90, s4, v102
	v_lshl_add_u64 v[88:89], v[88:89], 0, v[136:137]
	v_ashrrev_i32_e32 v91, 31, v90
	v_add_co_u32_e32 v88, vcc, s68, v88
	v_lshl_add_u64 v[90:91], v[90:91], 1, v[152:153]
	s_nop 0
	v_addc_co_u32_e32 v89, vcc, 0, v89, vcc
	v_add_co_u32_e32 v92, vcc, s43, v90
	v_mad_i64_i32 v[86:87], s[0:1], v102, s70, v[150:151]
	s_nop 0
	v_addc_co_u32_e32 v93, vcc, 0, v91, vcc
	v_add_co_u32_e32 v94, vcc, s73, v90
	s_waitcnt vmcnt(34) lgkmcnt(0)
	v_mov_b32_e32 v80, v240
	v_mov_b32_e32 v81, v241
	v_mov_b32_e32 v82, v242
	v_mov_b32_e32 v83, v243
	v_add_f32_e32 v80, v80, v81
	v_add_f32_e32 v80, v82, v80
	v_add_f32_e32 v82, v83, v80
	ds_bpermute_b32 v83, v163, v82
	v_addc_co_u32_e32 v95, vcc, 0, v91, vcc
	v_add_co_u32_e32 v96, vcc, s74, v90
	s_waitcnt lgkmcnt(0)
	v_add_f32_e32 v85, v82, v83
	v_addc_co_u32_e32 v97, vcc, 0, v91, vcc
	ds_bpermute_b32 v100, v155, v85
	v_add_co_u32_e32 v98, vcc, s37, v90
	s_waitcnt lgkmcnt(0)
	v_add_f32_e32 v85, v85, v100
	v_addc_co_u32_e32 v99, vcc, 0, v91, vcc
	v_add_co_u32_e32 v80, vcc, s54, v90
	v_fmamk_f32 v85, v85, 0x3b000000, v161
	s_nop 0
	v_addc_co_u32_e32 v81, vcc, 0, v91, vcc
	v_add_co_u32_e32 v82, vcc, s75, v90
	v_mul_f32_e32 v100, 0x4b800000, v85
	s_nop 0
	v_addc_co_u32_e32 v83, vcc, 0, v91, vcc
	v_cmp_gt_f32_e32 vcc, s69, v85
	s_nop 1
	v_cndmask_b32_e32 v85, v85, v100, vcc
	v_rsq_f32_e32 v85, v85
	v_add_co_u32_e64 v100, s[0:1], s76, v90
	v_mul_f32_e32 v102, 0x45800000, v85
	v_cndmask_b32_e32 v102, v85, v102, vcc
	v_pk_mul_f32 v[78:79], v[78:79], v[102:103] op_sel_hi:[1,0]
	v_pk_mul_f32 v[76:77], v[76:77], v[102:103] op_sel_hi:[1,0]
	v_pk_mul_f32 v[74:75], v[74:75], v[102:103] op_sel_hi:[1,0]
	v_pk_mul_f32 v[72:73], v[72:73], v[102:103] op_sel_hi:[1,0]
	v_mul_f32_e32 v68, v68, v102
	v_mul_f32_e32 v85, v64, v102
	v_mul_f32_e32 v69, v69, v102
	v_mul_f32_e32 v103, v65, v102
	v_mul_f32_e32 v70, v70, v102
	v_mul_f32_e32 v66, v66, v102
	v_mul_f32_e32 v71, v71, v102
	v_mul_f32_e32 v67, v67, v102
	v_cvt_pk_bf16_f32 v64, v76, v77
	v_cvt_pk_bf16_f32 v65, v78, v79
	v_bfe_u32 v76, v68, 16, 1
	v_bfe_u32 v77, v85, 16, 1
	v_bfe_u32 v78, v69, 16, 1
	v_bfe_u32 v79, v103, 16, 1
	v_bfe_u32 v102, v70, 16, 1
	v_bfe_u32 v104, v66, 16, 1
	v_bfe_u32 v105, v71, 16, 1
	v_bfe_u32 v106, v67, 16, 1
	global_store_dwordx2 v[86:87], v[64:65], off
	v_cvt_pk_bf16_f32 v64, v72, v73
	v_cvt_pk_bf16_f32 v65, v74, v75
	v_addc_co_u32_e64 v101, s[0:1], 0, v91, s[0:1]
	v_add3_u32 v68, v68, v76, s72
	v_add3_u32 v72, v85, v77, s72
	v_add3_u32 v69, v69, v78, s72
	v_add3_u32 v73, v103, v79, s72
	v_add3_u32 v70, v70, v102, s72
	v_add3_u32 v66, v66, v104, s72
	v_add3_u32 v71, v71, v105, s72
	v_add3_u32 v67, v67, v106, s72
	global_store_dwordx2 v[86:87], v[64:65], off offset:32
	global_store_short_d16_hi v[90:91], v68, off
	global_store_short_d16_hi v[92:93], v72, off
	global_store_short_d16_hi v[94:95], v69, off offset:512
	global_store_short_d16_hi v[96:97], v73, off offset:512
	global_store_short_d16_hi v[98:99], v70, off offset:1024
	global_store_short_d16_hi v[80:81], v66, off offset:1024
	global_store_short_d16_hi v[82:83], v71, off offset:1536
	global_store_short_d16_hi v[100:101], v67, off offset:1536
	v_add_u32_e32 v68, 0x90, v154
	v_ashrrev_i32_e32 v69, 31, v68
	v_lshlrev_b64 v[72:73], 7, v[68:69]
	v_lshl_add_u64 v[72:73], s[52:53], 0, v[72:73]
	v_add_u32_e32 v74, s4, v84
	v_lshl_add_u64 v[72:73], v[72:73], 0, v[136:137]
	v_ashrrev_i32_e32 v75, 31, v74
	v_add_co_u32_e32 v72, vcc, s68, v72
	v_lshl_add_u64 v[74:75], v[74:75], 1, v[152:153]
	s_nop 0
	v_addc_co_u32_e32 v73, vcc, 0, v73, vcc
	v_add_co_u32_e32 v76, vcc, s43, v74
	v_mad_i64_i32 v[70:71], s[0:1], v84, s70, v[150:151]
	s_nop 0
	v_addc_co_u32_e32 v77, vcc, 0, v75, vcc
	v_add_co_u32_e32 v78, vcc, s73, v74
	s_waitcnt vmcnt(43) lgkmcnt(0)
; DI bf16_t f2bf(float x) { unsigned u = __float_as_uint(x); u += 0x7fffu + ((u >> 16) & 1u); return (bf16_t)(u >> 16); }
; DI void st_bf16x4(bf16_t* p, f32x4 v) { u32x2 w; w.x = cvt_pk_bf16(v[0], v[1]); w.y = cvt_pk_bf16(v[2], v[3]); *(u32x2*)p = w; }
; DI float row_rstd(const unsigned char* ws, int row, int which, int fq) {
;     const f32x4 s4 = *(const f32x4*)((const float*)(ws + WS_SSQ) + (size_t)row * 32 + which * 16 + fq * 4);
;     float ss = s4[0] + s4[1] + s4[2] + s4[3];
;     ss += __shfl_xor(ss, 16); ss += __shfl_xor(ss, 32);
;     return rsqrtf(ss * (1.f / 512.f) + 1e-6f);
; }
;     DI void operator()(const f32x4 (&acc)[2][2][4][2], const Unit& u, int wr, int wc, int fr, int fq) const {
;     ...
;         for (int ai = 0; ai < 2; ++ai)
; #pragma unroll
;             for (int m = 0; m < 4; ++m) {
;                 const int row = u.pm * BM + ai * HALF + wr * 64 + m * 16 + fr;
;                 const int r = row - b * RB;
;                 const float rs = row_rstd(ws, row, 1, fq);
;                 {
;                     const f32x4 v0 = acc[ai][0][m][0] * rs, v1 = acc[ai][0][m][1] * rs;
;                     bf16_t* kp = Km + (size_t)row * 640 + head * 128 + wc * 32 + 4 * fq;
;                     st_bf16x4(kp, v0); st_bf16x4(kp + 16, v1);
;                 }
;                 {
;                     const f32x4 v0 = acc[ai][1][m][0] * rs, v1 = acc[ai][1][m][1] * rs;
;                     bf16_t* vt = (bf16_t*)(ws + WS_VTM) + ((size_t)b * 640 + head * 128 + wc * 32 + 4 * fq) * RB + r;
; #pragma unroll
;                     for (int j = 0; j < 4; ++j) { vt[(size_t)j * RB] = f2bf(v0[j]); vt[(size_t)(16 + j) * RB] = f2bf(v1[j]); }
;                 }
	v_mov_b32_e32 v64, v244
	v_mov_b32_e32 v65, v245
	v_mov_b32_e32 v66, v246
	v_mov_b32_e32 v67, v247
	v_add_f32_e32 v64, v64, v65
	v_add_f32_e32 v64, v66, v64
	v_add_f32_e32 v66, v67, v64
	ds_bpermute_b32 v67, v163, v66
	v_addc_co_u32_e32 v79, vcc, 0, v75, vcc
	v_add_co_u32_e32 v80, vcc, s74, v74
	s_waitcnt lgkmcnt(0)
	v_add_f32_e32 v69, v66, v67
	v_addc_co_u32_e32 v81, vcc, 0, v75, vcc
	ds_bpermute_b32 v84, v155, v69
	v_add_co_u32_e32 v82, vcc, s37, v74
	s_waitcnt lgkmcnt(0)
	v_add_f32_e32 v69, v69, v84
	v_addc_co_u32_e32 v83, vcc, 0, v75, vcc
	v_add_co_u32_e32 v64, vcc, s54, v74
	v_fmamk_f32 v69, v69, 0x3b000000, v161
	s_nop 0
	v_addc_co_u32_e32 v65, vcc, 0, v75, vcc
	v_add_co_u32_e32 v66, vcc, s75, v74
	v_mul_f32_e32 v84, 0x4b800000, v69
	s_nop 0
	v_addc_co_u32_e32 v67, vcc, 0, v75, vcc
	v_cmp_gt_f32_e32 vcc, s69, v69
	s_nop 1
	v_cndmask_b32_e32 v69, v69, v84, vcc
	v_rsq_f32_e32 v69, v69
	v_add_co_u32_e64 v84, s[0:1], s76, v74
	v_mul_f32_e32 v86, 0x45800000, v69
	v_cndmask_b32_e32 v86, v69, v86, vcc
	v_pk_mul_f32 v[62:63], v[62:63], v[86:87] op_sel_hi:[1,0]
	v_pk_mul_f32 v[60:61], v[60:61], v[86:87] op_sel_hi:[1,0]
	v_pk_mul_f32 v[58:59], v[58:59], v[86:87] op_sel_hi:[1,0]
	v_pk_mul_f32 v[56:57], v[56:57], v[86:87] op_sel_hi:[1,0]
	v_mul_f32_e32 v52, v52, v86
	v_mul_f32_e32 v69, v48, v86
	v_mul_f32_e32 v53, v53, v86
	v_mul_f32_e32 v87, v49, v86
	v_mul_f32_e32 v54, v54, v86
	v_mul_f32_e32 v50, v50, v86
	v_mul_f32_e32 v55, v55, v86
	v_mul_f32_e32 v51, v51, v86
	v_cvt_pk_bf16_f32 v48, v60, v61
	v_cvt_pk_bf16_f32 v49, v62, v63
	v_bfe_u32 v60, v52, 16, 1
	v_bfe_u32 v61, v69, 16, 1
	v_bfe_u32 v62, v53, 16, 1
	v_bfe_u32 v63, v87, 16, 1
	v_bfe_u32 v86, v54, 16, 1
	v_bfe_u32 v88, v50, 16, 1
	v_bfe_u32 v89, v55, 16, 1
	v_bfe_u32 v90, v51, 16, 1
	global_store_dwordx2 v[70:71], v[48:49], off
	v_cvt_pk_bf16_f32 v48, v56, v57
	v_cvt_pk_bf16_f32 v49, v58, v59
	v_addc_co_u32_e64 v85, s[0:1], 0, v75, s[0:1]
	v_add3_u32 v52, v52, v60, s72
	v_add3_u32 v56, v69, v61, s72
	v_add3_u32 v53, v53, v62, s72
	v_add3_u32 v57, v87, v63, s72
	v_add3_u32 v54, v54, v86, s72
	v_add3_u32 v50, v50, v88, s72
	v_add3_u32 v55, v55, v89, s72
	v_add3_u32 v51, v51, v90, s72
	global_store_dwordx2 v[70:71], v[48:49], off offset:32
	global_store_short_d16_hi v[74:75], v52, off
	global_store_short_d16_hi v[76:77], v56, off
	global_store_short_d16_hi v[78:79], v53, off offset:512
	global_store_short_d16_hi v[80:81], v57, off offset:512
	global_store_short_d16_hi v[82:83], v54, off offset:1024
	global_store_short_d16_hi v[64:65], v50, off offset:1024
	global_store_short_d16_hi v[66:67], v55, off offset:1536
	global_store_short_d16_hi v[84:85], v51, off offset:1536
	v_add_u32_e32 v52, 0xa0, v154
	v_ashrrev_i32_e32 v53, 31, v52
	v_lshlrev_b64 v[56:57], 7, v[52:53]
	v_lshl_add_u64 v[56:57], s[52:53], 0, v[56:57]
	v_add_u32_e32 v58, s4, v68
	v_lshl_add_u64 v[56:57], v[56:57], 0, v[136:137]
	v_ashrrev_i32_e32 v59, 31, v58
	v_add_co_u32_e32 v56, vcc, s68, v56
	v_lshl_add_u64 v[58:59], v[58:59], 1, v[152:153]
	s_nop 0
	v_addc_co_u32_e32 v57, vcc, 0, v57, vcc
	v_add_co_u32_e32 v60, vcc, s43, v58
	v_mad_i64_i32 v[54:55], s[0:1], v68, s70, v[150:151]
	s_nop 0
	v_addc_co_u32_e32 v61, vcc, 0, v59, vcc
	v_add_co_u32_e32 v62, vcc, s73, v58
	s_waitcnt vmcnt(52) lgkmcnt(0)
	v_mov_b32_e32 v48, v248
	v_mov_b32_e32 v49, v249
	v_mov_b32_e32 v50, v250
	v_mov_b32_e32 v51, v251
	v_add_f32_e32 v48, v48, v49
	v_add_f32_e32 v48, v50, v48
	v_add_f32_e32 v50, v51, v48
	ds_bpermute_b32 v51, v163, v50
	v_addc_co_u32_e32 v63, vcc, 0, v59, vcc
	v_add_co_u32_e32 v64, vcc, s74, v58
	s_waitcnt lgkmcnt(0)
	v_add_f32_e32 v53, v50, v51
	v_addc_co_u32_e32 v65, vcc, 0, v59, vcc
	ds_bpermute_b32 v68, v155, v53
	v_add_co_u32_e32 v66, vcc, s37, v58
	s_waitcnt lgkmcnt(0)
	v_add_f32_e32 v53, v53, v68
	v_addc_co_u32_e32 v67, vcc, 0, v59, vcc
	v_add_co_u32_e32 v48, vcc, s54, v58
	v_fmamk_f32 v53, v53, 0x3b000000, v161
	s_nop 0
	v_addc_co_u32_e32 v49, vcc, 0, v59, vcc
	v_add_co_u32_e32 v50, vcc, s75, v58
	v_mul_f32_e32 v68, 0x4b800000, v53
	s_nop 0
	v_addc_co_u32_e32 v51, vcc, 0, v59, vcc
	v_cmp_gt_f32_e32 vcc, s69, v53
	s_nop 1
	v_cndmask_b32_e32 v53, v53, v68, vcc
	v_rsq_f32_e32 v53, v53
	v_add_co_u32_e64 v68, s[0:1], s76, v58
	v_mul_f32_e32 v70, 0x45800000, v53
	v_cndmask_b32_e32 v70, v53, v70, vcc
	v_pk_mul_f32 v[46:47], v[46:47], v[70:71] op_sel_hi:[1,0]
	v_pk_mul_f32 v[44:45], v[44:45], v[70:71] op_sel_hi:[1,0]
	v_pk_mul_f32 v[42:43], v[42:43], v[70:71] op_sel_hi:[1,0]
	v_pk_mul_f32 v[40:41], v[40:41], v[70:71] op_sel_hi:[1,0]
	v_mul_f32_e32 v36, v36, v70
	v_mul_f32_e32 v53, v32, v70
	v_mul_f32_e32 v37, v37, v70
	v_mul_f32_e32 v71, v33, v70
	v_mul_f32_e32 v38, v38, v70
	v_mul_f32_e32 v34, v34, v70
	v_mul_f32_e32 v39, v39, v70
	v_mul_f32_e32 v35, v35, v70
	v_cvt_pk_bf16_f32 v32, v44, v45
	v_cvt_pk_bf16_f32 v33, v46, v47
	v_bfe_u32 v44, v36, 16, 1
	v_bfe_u32 v45, v53, 16, 1
	v_bfe_u32 v46, v37, 16, 1
	v_bfe_u32 v47, v71, 16, 1
	v_bfe_u32 v70, v38, 16, 1
	v_bfe_u32 v72, v34, 16, 1
	v_bfe_u32 v73, v39, 16, 1
	v_bfe_u32 v74, v35, 16, 1
	global_store_dwordx2 v[54:55], v[32:33], off
	v_cvt_pk_bf16_f32 v32, v40, v41
	v_cvt_pk_bf16_f32 v33, v42, v43
	v_addc_co_u32_e64 v69, s[0:1], 0, v59, s[0:1]
	v_add3_u32 v36, v36, v44, s72
	v_add3_u32 v40, v53, v45, s72
	v_add3_u32 v37, v37, v46, s72
	v_add3_u32 v41, v71, v47, s72
	v_add3_u32 v38, v38, v70, s72
	v_add3_u32 v34, v34, v72, s72
	v_add3_u32 v39, v39, v73, s72
	v_add3_u32 v35, v35, v74, s72
	global_store_dwordx2 v[54:55], v[32:33], off offset:32
	global_store_short_d16_hi v[58:59], v36, off
	global_store_short_d16_hi v[60:61], v40, off
	global_store_short_d16_hi v[62:63], v37, off offset:512
	global_store_short_d16_hi v[64:65], v41, off offset:512
	global_store_short_d16_hi v[66:67], v38, off offset:1024
	global_store_short_d16_hi v[48:49], v34, off offset:1024
	global_store_short_d16_hi v[50:51], v39, off offset:1536
	global_store_short_d16_hi v[68:69], v35, off offset:1536
	v_add_u32_e32 v36, 0xb0, v154
	v_ashrrev_i32_e32 v37, 31, v36
	v_lshlrev_b64 v[40:41], 7, v[36:37]
	v_lshl_add_u64 v[40:41], s[52:53], 0, v[40:41]
	v_add_u32_e32 v42, s4, v52
	v_lshl_add_u64 v[40:41], v[40:41], 0, v[136:137]
	v_ashrrev_i32_e32 v43, 31, v42
	v_add_co_u32_e32 v40, vcc, s68, v40
	v_lshl_add_u64 v[42:43], v[42:43], 1, v[152:153]
	s_nop 0
	v_addc_co_u32_e32 v41, vcc, 0, v41, vcc
	v_add_co_u32_e32 v44, vcc, s43, v42
	v_mad_i64_i32 v[38:39], s[0:1], v52, s70, v[150:151]
	s_nop 0
	v_addc_co_u32_e32 v45, vcc, 0, v43, vcc
	v_add_co_u32_e32 v46, vcc, s73, v42
	s_waitcnt vmcnt(41) lgkmcnt(0)
; DI bf16_t f2bf(float x) { unsigned u = __float_as_uint(x); u += 0x7fffu + ((u >> 16) & 1u); return (bf16_t)(u >> 16); }
; #define G_WAIT_V(n) asm volatile("s_waitcnt vmcnt(" #n ")" ::: "memory")
; #define G_BAR __builtin_amdgcn_s_barrier()
; DI void st_bf16x4(bf16_t* p, f32x4 v) { u32x2 w; w.x = cvt_pk_bf16(v[0], v[1]); w.y = cvt_pk_bf16(v[2], v[3]); *(u32x2*)p = w; }
; template <class Epi, bool PERMROWS = false>
; DI void gemm_phase(LAS unsigned char* lds, const bf16_t* A, int lda, const bf16_t* Bt, int K, const Sched& S, const Epi& E) {
;     ...
;         if (!has_next) break;
; #pragma unroll
;         for (int a = 0; a < 2; ++a)
; #pragma unroll
;             for (int b = 0; b < 2; ++b)
; #pragma unroll
;                 for (int m = 0; m < 4; ++m)
; #pragma unroll
;                     for (int n = 0; n < 2; ++n) acc[a][b][m][n] = (f32x4){0.f, 0.f, 0.f, 0.f};
;         cur = nxt; cA = nA; cB = nB; ++ui; nt = cur.kq >= 0 ? ntQ : ntF;
;     }
;     G_WAIT_V(0);
;     if (wr == 0) G_BAR;
;     G_BAR;
;     DI void operator()(const f32x4 (&acc)[2][2][4][2], const Unit& u, int wr, int wc, int fr, int fq) const {
;     ...
;                 const int row = u.pm * BM + ai * HALF + wr * 64 + m * 16 + fr;
;                 const int r = row - b * RB;
;                 const float rs = row_rstd(ws, row, 1, fq);
;                 {
;                     const f32x4 v0 = acc[ai][0][m][0] * rs, v1 = acc[ai][0][m][1] * rs;
;                     bf16_t* kp = Km + (size_t)row * 640 + head * 128 + wc * 32 + 4 * fq;
;                     st_bf16x4(kp, v0); st_bf16x4(kp + 16, v1);
;                 }
;                 {
;                     const f32x4 v0 = acc[ai][1][m][0] * rs, v1 = acc[ai][1][m][1] * rs;
;                     bf16_t* vt = (bf16_t*)(ws + WS_VTM) + ((size_t)b * 640 + head * 128 + wc * 32 + 4 * fq) * RB + r;
; #pragma unroll
;                     for (int j = 0; j < 4; ++j) { vt[(size_t)j * RB] = f2bf(v0[j]); vt[(size_t)(16 + j) * RB] = f2bf(v1[j]); }
;                 }
	v_mov_b32_e32 v32, v232
	v_mov_b32_e32 v33, v233
	v_mov_b32_e32 v34, v234
	v_mov_b32_e32 v35, v235
	v_add_f32_e32 v32, v32, v33
	v_add_f32_e32 v32, v34, v32
	v_add_f32_e32 v34, v35, v32
	ds_bpermute_b32 v35, v163, v34
	v_addc_co_u32_e32 v47, vcc, 0, v43, vcc
	v_add_co_u32_e32 v48, vcc, s74, v42
	s_waitcnt lgkmcnt(0)
	v_add_f32_e32 v37, v34, v35
	v_addc_co_u32_e32 v49, vcc, 0, v43, vcc
	ds_bpermute_b32 v52, v155, v37
	v_add_co_u32_e32 v50, vcc, s37, v42
	s_waitcnt lgkmcnt(0)
	v_add_f32_e32 v37, v37, v52
	v_addc_co_u32_e32 v51, vcc, 0, v43, vcc
	v_add_co_u32_e32 v32, vcc, s54, v42
	v_fmamk_f32 v37, v37, 0x3b000000, v161
	s_nop 0
	v_addc_co_u32_e32 v33, vcc, 0, v43, vcc
	v_add_co_u32_e32 v34, vcc, s75, v42
	v_mul_f32_e32 v52, 0x4b800000, v37
	s_nop 0
	v_addc_co_u32_e32 v35, vcc, 0, v43, vcc
	v_cmp_gt_f32_e32 vcc, s69, v37
	s_nop 1
	v_cndmask_b32_e32 v37, v37, v52, vcc
	v_rsq_f32_e32 v37, v37
	v_add_co_u32_e64 v52, s[0:1], s76, v42
	v_mul_f32_e32 v54, 0x45800000, v37
	v_cndmask_b32_e32 v54, v37, v54, vcc
	v_pk_mul_f32 v[30:31], v[30:31], v[54:55] op_sel_hi:[1,0]
	v_pk_mul_f32 v[28:29], v[28:29], v[54:55] op_sel_hi:[1,0]
	v_pk_mul_f32 v[26:27], v[26:27], v[54:55] op_sel_hi:[1,0]
	v_pk_mul_f32 v[24:25], v[24:25], v[54:55] op_sel_hi:[1,0]
	v_mul_f32_e32 v20, v20, v54
	v_mul_f32_e32 v37, v16, v54
	v_mul_f32_e32 v21, v21, v54
	v_mul_f32_e32 v55, v17, v54
	v_mul_f32_e32 v22, v22, v54
	v_mul_f32_e32 v18, v18, v54
	v_mul_f32_e32 v23, v23, v54
	v_mul_f32_e32 v19, v19, v54
	v_cvt_pk_bf16_f32 v16, v28, v29
	v_cvt_pk_bf16_f32 v17, v30, v31
	v_bfe_u32 v28, v20, 16, 1
	v_bfe_u32 v29, v37, 16, 1
	v_bfe_u32 v30, v21, 16, 1
	v_bfe_u32 v31, v55, 16, 1
	v_bfe_u32 v54, v22, 16, 1
	v_bfe_u32 v56, v18, 16, 1
	v_bfe_u32 v57, v23, 16, 1
	v_bfe_u32 v58, v19, 16, 1
	global_store_dwordx2 v[38:39], v[16:17], off
	v_cvt_pk_bf16_f32 v16, v24, v25
	v_cvt_pk_bf16_f32 v17, v26, v27
	v_addc_co_u32_e64 v53, s[0:1], 0, v43, s[0:1]
	v_add3_u32 v20, v20, v28, s72
	v_add3_u32 v24, v37, v29, s72
	v_add3_u32 v21, v21, v30, s72
	v_add3_u32 v25, v55, v31, s72
	v_add3_u32 v22, v22, v54, s72
	v_add3_u32 v18, v18, v56, s72
	v_add3_u32 v23, v23, v57, s72
	v_add3_u32 v19, v19, v58, s72
	global_store_dwordx2 v[38:39], v[16:17], off offset:32
	global_store_short_d16_hi v[42:43], v20, off
	global_store_short_d16_hi v[44:45], v24, off
	global_store_short_d16_hi v[46:47], v21, off offset:512
	global_store_short_d16_hi v[48:49], v25, off offset:512
	global_store_short_d16_hi v[50:51], v22, off offset:1024
	global_store_short_d16_hi v[32:33], v18, off offset:1024
	global_store_short_d16_hi v[34:35], v23, off offset:1536
	global_store_short_d16_hi v[52:53], v19, off offset:1536
	v_add_u32_e32 v22, s4, v36
	v_ashrrev_i32_e32 v23, 31, v22
	v_lshl_add_u64 v[22:23], v[22:23], 1, v[152:153]
	v_add_co_u32_e32 v24, vcc, s43, v22
	s_and_b64 s[0:1], exec, s[2:3]
	s_nop 0
	v_addc_co_u32_e32 v25, vcc, 0, v23, vcc
	v_add_co_u32_e32 v26, vcc, s73, v22
	v_mad_i64_i32 v[20:21], s[2:3], v36, s70, v[150:151]
	s_nop 0
	v_addc_co_u32_e32 v27, vcc, 0, v23, vcc
	v_add_co_u32_e32 v28, vcc, s74, v22
	s_waitcnt vmcnt(40) lgkmcnt(0)
	v_mov_b32_e32 v16, v236
	v_mov_b32_e32 v17, v237
	v_mov_b32_e32 v18, v238
	v_mov_b32_e32 v19, v239
	v_add_f32_e32 v16, v16, v17
	v_add_f32_e32 v16, v18, v16
	v_add_f32_e32 v17, v19, v16
	ds_bpermute_b32 v18, v163, v17
	v_addc_co_u32_e32 v29, vcc, 0, v23, vcc
	v_add_co_u32_e32 v30, vcc, s37, v22
	s_waitcnt lgkmcnt(0)
	v_add_f32_e32 v19, v17, v18
	ds_bpermute_b32 v34, v155, v19
	v_addc_co_u32_e32 v31, vcc, 0, v23, vcc
	v_add_co_u32_e32 v32, vcc, s54, v22
	s_waitcnt lgkmcnt(0)
	v_add_f32_e32 v19, v19, v34
	v_fmamk_f32 v19, v19, 0x3b000000, v161
	v_mul_f32_e32 v34, 0x4b800000, v19
	v_cmp_gt_f32_e64 s[2:3], s69, v19
	v_addc_co_u32_e32 v33, vcc, 0, v23, vcc
	s_nop 0
	v_cndmask_b32_e64 v19, v19, v34, s[2:3]
	v_rsq_f32_e32 v34, v19
	v_add_co_u32_e32 v16, vcc, 0x3000, v22
	v_mul_f32_e32 v35, 0x45800000, v34
	s_nop 0
	v_addc_co_u32_e32 v17, vcc, 0, v23, vcc
	v_add_co_u32_e32 v18, vcc, 0x15000, v22
	v_cndmask_b32_e64 v34, v34, v35, s[2:3]
	s_nop 0
	v_addc_co_u32_e32 v19, vcc, 0, v23, vcc
	v_pk_mul_f32 v[14:15], v[14:15], v[34:35] op_sel_hi:[1,0]
	v_pk_mul_f32 v[12:13], v[12:13], v[34:35] op_sel_hi:[1,0]
	v_pk_mul_f32 v[10:11], v[10:11], v[34:35] op_sel_hi:[1,0]
	v_pk_mul_f32 v[8:9], v[8:9], v[34:35] op_sel_hi:[1,0]
	v_mul_f32_e32 v4, v4, v34
	v_mul_f32_e32 v35, v0, v34
	v_mul_f32_e32 v5, v5, v34
	v_mul_f32_e32 v36, v1, v34
	v_mul_f32_e32 v6, v6, v34
	v_mul_f32_e32 v2, v2, v34
	v_mul_f32_e32 v7, v7, v34
	v_mul_f32_e32 v3, v3, v34
	v_cvt_pk_bf16_f32 v0, v12, v13
	v_cvt_pk_bf16_f32 v1, v14, v15
	v_bfe_u32 v12, v4, 16, 1
	v_bfe_u32 v13, v35, 16, 1
	v_bfe_u32 v14, v5, 16, 1
	v_bfe_u32 v15, v36, 16, 1
	v_bfe_u32 v34, v6, 16, 1
	v_bfe_u32 v37, v2, 16, 1
	v_bfe_u32 v38, v7, 16, 1
	v_bfe_u32 v39, v3, 16, 1
	global_store_dwordx2 v[20:21], v[0:1], off
	v_cvt_pk_bf16_f32 v0, v8, v9
	v_cvt_pk_bf16_f32 v1, v10, v11
	s_mov_b64 vcc, s[0:1]
	v_add3_u32 v4, v4, v12, s72
	v_add3_u32 v8, v35, v13, s72
	v_add3_u32 v5, v5, v14, s72
	v_add3_u32 v9, v36, v15, s72
	v_add3_u32 v6, v6, v34, s72
	v_add3_u32 v2, v2, v37, s72
	v_add3_u32 v7, v7, v38, s72
	v_add3_u32 v3, v3, v39, s72
	global_store_dwordx2 v[20:21], v[0:1], off offset:32
	global_store_short_d16_hi v[22:23], v4, off
	global_store_short_d16_hi v[24:25], v8, off
	global_store_short_d16_hi v[26:27], v5, off offset:512
	global_store_short_d16_hi v[28:29], v9, off offset:512
	global_store_short_d16_hi v[30:31], v6, off offset:1024
	global_store_short_d16_hi v[32:33], v2, off offset:1024
	global_store_short_d16_hi v[16:17], v7, off offset:1536
	global_store_short_d16_hi v[18:19], v3, off offset:1536
	s_cbranch_vccz .LBB0_2509
	s_waitcnt vmcnt(0)
	s_cmpk_gt_u32 s6, 0xff
	s_cbranch_scc1 .LBB0_2522
	s_barrier
